# v19 + lean LDS-DMA issue in 7 GEMM K-loops (rw_gemm1, ret_inproj, ret_state, gm_inproj, 3 out-projections): per-lane source addresses kept in VGPRs and stepped by +0x80, m0 from SALU adds; no per-load
# speedup vs baseline: 1.0137x; 1.0053x over previous
.LBB0_302:
	s_mul_i32 s1, s10, s9
	s_sub_i32 s1, s11, s1
	s_add_i32 s8, s8, s1
	s_lshl_b32 s38, s8, 7
	s_lshl_b32 s40, s10, 7
	s_lshl_b32 s11, s0, 1
	s_add_u32 s8, s86, s11
	s_addc_u32 s9, s87, 0
	s_ashr_i32 s39, s38, 31
	s_lshl_b64 s[0:1], s[38:39], 11
	s_add_u32 s8, s8, s0
	s_addc_u32 s9, s9, s1
	v_lshl_add_u64 v[0:1], v[72:73], 1, s[8:9]
	v_readfirstlane_b32 s8, v84
	v_add_u32_e32 v6, 0x1000, v84
	v_lshl_add_u64 v[0:1], v[0:1], 0, v[68:69]
	s_mov_b32 m0, s8
	s_mov_b64 s[18:19], 0x10000
	v_readfirstlane_b32 s8, v6
	v_add_u32_e32 v6, 0x2000, v84
	global_load_lds_dwordx4 v[0:1], off
	v_lshl_add_u64 v[4:5], v[0:1], 0, s[18:19]
	s_mov_b32 m0, s8
	v_readfirstlane_b32 s8, v6
	global_load_lds_dwordx4 v[4:5], off
	v_lshl_add_u64 v[4:5], v[0:1], 0, s[28:29]
	s_mov_b32 m0, s8
	s_mov_b64 s[22:23], 0x30000
	global_load_lds_dwordx4 v[4:5], off
	v_add_u32_e32 v4, 0x3000, v84
	v_lshl_add_u64 v[0:1], v[0:1], 0, s[22:23]
	v_readfirstlane_b32 s8, v4
	s_mov_b32 m0, s8
	s_ashr_i32 s41, s40, 31
	global_load_lds_dwordx4 v[0:1], off
	v_add_u32_e32 v0, 0x8000, v84
	s_lshl_b64 s[12:13], s[40:41], 11
	v_readfirstlane_b32 s8, v0
	v_add_u32_e32 v4, 0x9000, v84
	v_lshl_add_u64 v[2:3], v[74:75], 0, s[12:13]
	s_mov_b32 m0, s8
	v_readfirstlane_b32 s8, v4
	v_add_u32_e32 v4, 0xa000, v84
	global_load_lds_dwordx4 v[2:3], off
	v_lshl_add_u64 v[0:1], v[2:3], 0, s[18:19]
	s_mov_b32 m0, s8
	v_readfirstlane_b32 s8, v4
	global_load_lds_dwordx4 v[0:1], off
	v_lshl_add_u64 v[0:1], v[2:3], 0, s[28:29]
	s_mov_b32 m0, s8
	s_add_u32 s0, s0, s11
	global_load_lds_dwordx4 v[0:1], off
	v_lshl_add_u64 v[0:1], v[2:3], 0, s[22:23]
	v_add_u32_e32 v2, 0xb000, v84
	s_addc_u32 s1, s1, 0
	v_readfirstlane_b32 s8, v2
	s_mov_b32 m0, s8
	v_lshl_add_u64 v[78:79], v[76:77], 0, s[0:1]
	global_load_lds_dwordx4 v[0:1], off
	s_waitcnt vmcnt(0)
	v_mov_b32_e32 v0, 0
	v_lshl_add_u64 v[80:81], v[76:77], 0, s[12:13]
	s_mov_b32 s0, 0
	v_mov_b32_e32 v1, v0
	v_mov_b32_e32 v2, v0
	v_mov_b32_e32 v3, v0
	v_mov_b32_e32 v4, v0
	v_mov_b32_e32 v5, v0
	v_mov_b32_e32 v6, v0
	v_mov_b32_e32 v7, v0
	v_mov_b32_e32 v8, v0
	v_mov_b32_e32 v9, v0
	v_mov_b32_e32 v10, v0
	v_mov_b32_e32 v11, v0
	v_mov_b32_e32 v12, v0
	v_mov_b32_e32 v13, v0
	v_mov_b32_e32 v14, v0
	v_mov_b32_e32 v15, v0
	v_mov_b32_e32 v16, v0
	v_mov_b32_e32 v17, v0
	v_mov_b32_e32 v18, v0
	v_mov_b32_e32 v19, v0
	v_mov_b32_e32 v20, v0
	v_mov_b32_e32 v21, v0
	v_mov_b32_e32 v22, v0
	v_mov_b32_e32 v23, v0
	v_mov_b32_e32 v24, v0
	v_mov_b32_e32 v25, v0
	v_mov_b32_e32 v26, v0
	v_mov_b32_e32 v27, v0
	v_mov_b32_e32 v28, v0
	v_mov_b32_e32 v29, v0
	v_mov_b32_e32 v30, v0
	v_mov_b32_e32 v31, v0
	v_mov_b32_e32 v32, v0
	v_mov_b32_e32 v33, v0
	v_mov_b32_e32 v34, v0
	v_mov_b32_e32 v35, v0
	v_mov_b32_e32 v36, v0
	v_mov_b32_e32 v37, v0
	v_mov_b32_e32 v38, v0
	v_mov_b32_e32 v39, v0
	v_mov_b32_e32 v40, v0
	v_mov_b32_e32 v41, v0
	v_mov_b32_e32 v42, v0
	v_mov_b32_e32 v43, v0
	v_mov_b32_e32 v44, v0
	v_mov_b32_e32 v45, v0
	v_mov_b32_e32 v46, v0
	v_mov_b32_e32 v47, v0
	v_mov_b32_e32 v48, v0
	v_mov_b32_e32 v49, v0
	v_mov_b32_e32 v50, v0
	v_mov_b32_e32 v51, v0
	v_mov_b32_e32 v52, v0
	v_mov_b32_e32 v53, v0
	v_mov_b32_e32 v54, v0
	v_mov_b32_e32 v55, v0
	v_mov_b32_e32 v56, v0
	v_mov_b32_e32 v57, v0
	v_mov_b32_e32 v58, v0
	v_mov_b32_e32 v59, v0
	v_mov_b32_e32 v60, v0
	v_mov_b32_e32 v61, v0
	v_mov_b32_e32 v62, v0
	v_mov_b32_e32 v63, v0
	v_lshl_add_u64 v[82:83], v[78:79], 0, s[20:21]
	s_mov_b64 s[8:9], 0xf500080
	v_lshl_add_u64 v[96:97], v[82:83], 0, s[8:9]
	s_mov_b64 s[8:9], 0xf510080
	v_mov_b32_e32 v184, v96
	v_mov_b32_e32 v185, v97
	v_lshl_add_u64 v[96:97], v[82:83], 0, s[8:9]
	s_mov_b64 s[8:9], 0xf520080
	v_mov_b32_e32 v186, v96
	v_mov_b32_e32 v187, v97
	v_lshl_add_u64 v[96:97], v[82:83], 0, s[8:9]
	s_mov_b64 s[8:9], 0xf530080
	v_mov_b32_e32 v188, v96
	v_mov_b32_e32 v189, v97
	v_lshl_add_u64 v[82:83], v[82:83], 0, s[8:9]
	s_mov_b64 s[8:9], 0x3040080
	v_mov_b32_e32 v190, v82
	v_mov_b32_e32 v191, v83
	v_lshl_add_u64 v[82:83], v[80:81], 0, s[20:21]
	v_lshl_add_u64 v[96:97], v[82:83], 0, s[8:9]
	s_mov_b64 s[8:9], 0x3050080
	v_mov_b32_e32 v192, v96
	v_mov_b32_e32 v193, v97
	v_lshl_add_u64 v[96:97], v[82:83], 0, s[8:9]
	s_mov_b64 s[8:9], 0x3060080
	v_mov_b32_e32 v194, v96
	v_mov_b32_e32 v195, v97
	v_lshl_add_u64 v[96:97], v[82:83], 0, s[8:9]
	s_mov_b64 s[8:9], 0x3070080
	v_lshl_add_u64 v[82:83], v[82:83], 0, s[8:9]
	v_mov_b32_e32 v196, v96
	v_mov_b32_e32 v197, v97
	v_mov_b32_e32 v198, v82
	v_mov_b32_e32 v199, v83
	v_readfirstlane_b32 s100, v84
	s_mov_b64 vcc, 0x80
	s_waitcnt vmcnt(0) lgkmcnt(0)
	s_barrier
.LBB0_303:
	s_and_b32 s1, s0, 0x2000
	s_xor_b32 s8, s1, 0x2000
	s_lshl_b32 s101, s8, 1
	s_add_u32 s101, s101, s100
	s_add_u32 m0, s101, 0x0
	s_nop 0
	global_load_lds_dwordx4 v[184:185], off
	s_add_u32 m0, s101, 0x1000
	v_lshl_add_u64 v[184:185], v[184:185], 0, vcc
	global_load_lds_dwordx4 v[186:187], off
	s_add_u32 m0, s101, 0x2000
	v_lshl_add_u64 v[186:187], v[186:187], 0, vcc
	global_load_lds_dwordx4 v[188:189], off
	s_add_u32 m0, s101, 0x3000
	v_lshl_add_u64 v[188:189], v[188:189], 0, vcc
	global_load_lds_dwordx4 v[190:191], off
	s_add_u32 m0, s101, 0x8000
	v_lshl_add_u64 v[190:191], v[190:191], 0, vcc
	global_load_lds_dwordx4 v[192:193], off
	s_add_u32 m0, s101, 0x9000
	v_lshl_add_u64 v[192:193], v[192:193], 0, vcc
	global_load_lds_dwordx4 v[194:195], off
	s_add_u32 m0, s101, 0xa000
	v_lshl_add_u64 v[194:195], v[194:195], 0, vcc
	global_load_lds_dwordx4 v[196:197], off
	s_add_u32 m0, s101, 0xb000
	v_lshl_add_u64 v[196:197], v[196:197], 0, vcc
	global_load_lds_dwordx4 v[198:199], off
	v_lshl_add_u64 v[198:199], v[198:199], 0, vcc
	s_lshl_b32 s1, s1, 1
	v_add_u32_e32 v82, s1, v86
	v_add_u32_e32 v83, s1, v85
	v_add_u32_e32 v95, v82, v93
	ds_read_b128 v[96:99], v95
	ds_read_b128 v[100:103], v95 offset:2048
	ds_read_b128 v[120:123], v95 offset:4096
	ds_read_b128 v[124:127], v95 offset:6144
	v_add_u32_e32 v95, v83, v93
	ds_read_b128 v[128:131], v95 offset:32768
	ds_read_b128 v[132:135], v95 offset:34816
	ds_read_b128 v[136:139], v95 offset:36864
	ds_read_b128 v[140:143], v95 offset:38912
	s_setprio 1
	s_waitcnt lgkmcnt(0)
	v_mfma_f32_16x16x32_bf16 v[60:63], v[128:131], v[96:99], v[60:63]
	v_mfma_f32_16x16x32_bf16 v[56:59], v[132:135], v[96:99], v[56:59]
	v_mfma_f32_16x16x32_bf16 v[52:55], v[136:139], v[96:99], v[52:55]
	v_mfma_f32_16x16x32_bf16 v[48:51], v[140:143], v[96:99], v[48:51]
	v_mfma_f32_16x16x32_bf16 v[44:47], v[128:131], v[100:103], v[44:47]
	v_mfma_f32_16x16x32_bf16 v[40:43], v[132:135], v[100:103], v[40:43]
	v_mfma_f32_16x16x32_bf16 v[36:39], v[136:139], v[100:103], v[36:39]
	v_mfma_f32_16x16x32_bf16 v[32:35], v[140:143], v[100:103], v[32:35]
	v_mfma_f32_16x16x32_bf16 v[28:31], v[128:131], v[120:123], v[28:31]
	v_mfma_f32_16x16x32_bf16 v[24:27], v[132:135], v[120:123], v[24:27]
	v_mfma_f32_16x16x32_bf16 v[20:23], v[136:139], v[120:123], v[20:23]
	v_mfma_f32_16x16x32_bf16 v[16:19], v[140:143], v[120:123], v[16:19]
	v_mfma_f32_16x16x32_bf16 v[12:15], v[128:131], v[124:127], v[12:15]
	v_mfma_f32_16x16x32_bf16 v[8:11], v[132:135], v[124:127], v[8:11]
	v_mfma_f32_16x16x32_bf16 v[4:7], v[136:139], v[124:127], v[4:7]
	v_mfma_f32_16x16x32_bf16 v[0:3], v[140:143], v[124:127], v[0:3]
	s_setprio 0
	v_add_u32_e32 v82, v82, v94
	ds_read_b128 v[96:99], v82
	ds_read_b128 v[100:103], v82 offset:2048
	ds_read_b128 v[120:123], v82 offset:4096
	ds_read_b128 v[124:127], v82 offset:6144
	v_add_u32_e32 v82, v83, v94
	ds_read_b128 v[128:131], v82 offset:32768
	ds_read_b128 v[132:135], v82 offset:34816
	ds_read_b128 v[136:139], v82 offset:36864
	ds_read_b128 v[140:143], v82 offset:38912
	s_setprio 1
	s_waitcnt lgkmcnt(0)
	v_mfma_f32_16x16x32_bf16 v[60:63], v[128:131], v[96:99], v[60:63]
	v_mfma_f32_16x16x32_bf16 v[56:59], v[132:135], v[96:99], v[56:59]
	v_mfma_f32_16x16x32_bf16 v[52:55], v[136:139], v[96:99], v[52:55]
	v_mfma_f32_16x16x32_bf16 v[48:51], v[140:143], v[96:99], v[48:51]
	v_mfma_f32_16x16x32_bf16 v[44:47], v[128:131], v[100:103], v[44:47]
	v_mfma_f32_16x16x32_bf16 v[40:43], v[132:135], v[100:103], v[40:43]
	v_mfma_f32_16x16x32_bf16 v[36:39], v[136:139], v[100:103], v[36:39]
	v_mfma_f32_16x16x32_bf16 v[32:35], v[140:143], v[100:103], v[32:35]
	v_mfma_f32_16x16x32_bf16 v[28:31], v[128:131], v[120:123], v[28:31]
	v_mfma_f32_16x16x32_bf16 v[24:27], v[132:135], v[120:123], v[24:27]
	v_mfma_f32_16x16x32_bf16 v[20:23], v[136:139], v[120:123], v[20:23]
	v_mfma_f32_16x16x32_bf16 v[16:19], v[140:143], v[120:123], v[16:19]
	v_mfma_f32_16x16x32_bf16 v[12:15], v[128:131], v[124:127], v[12:15]
	v_mfma_f32_16x16x32_bf16 v[8:11], v[132:135], v[124:127], v[8:11]
	v_mfma_f32_16x16x32_bf16 v[4:7], v[136:139], v[124:127], v[4:7]
	v_mfma_f32_16x16x32_bf16 v[0:3], v[140:143], v[124:127], v[0:3]
	s_setprio 0
	s_addk_i32 s0, 0x2000
	s_waitcnt vmcnt(0)
	s_add_u32 s20, s20, 0x80
	s_addc_u32 s21, s21, 0
	s_cmpk_lg_i32 s20, 0x780
	s_waitcnt vmcnt(0)
	s_barrier
	s_cbranch_scc1 .LBB0_303
	ds_read_b128 v[78:81], v89 offset:55296
	ds_read_b128 v[96:99], v89 offset:53248
	ds_read_b128 v[100:103], v89 offset:51200
	ds_read_b128 v[120:123], v89 offset:49152
	ds_read_b128 v[124:127], v90 offset:22528
	ds_read_b128 v[128:131], v90 offset:20480
	ds_read_b128 v[132:135], v90 offset:18432
	ds_read_b128 v[136:139], v90 offset:16384
	s_setprio 1
	s_waitcnt lgkmcnt(0)
	v_mfma_f32_16x16x32_bf16 v[60:63], v[120:123], v[136:139], v[60:63]
	v_mfma_f32_16x16x32_bf16 v[56:59], v[100:103], v[136:139], v[56:59]
	v_mfma_f32_16x16x32_bf16 v[52:55], v[96:99], v[136:139], v[52:55]
	v_mfma_f32_16x16x32_bf16 v[48:51], v[78:81], v[136:139], v[48:51]
	v_mfma_f32_16x16x32_bf16 v[44:47], v[120:123], v[132:135], v[44:47]
	v_mfma_f32_16x16x32_bf16 v[40:43], v[100:103], v[132:135], v[40:43]
	v_mfma_f32_16x16x32_bf16 v[36:39], v[96:99], v[132:135], v[36:39]
	v_mfma_f32_16x16x32_bf16 v[32:35], v[78:81], v[132:135], v[32:35]
	v_mfma_f32_16x16x32_bf16 v[28:31], v[120:123], v[128:131], v[28:31]
	v_mfma_f32_16x16x32_bf16 v[24:27], v[100:103], v[128:131], v[24:27]
	v_mfma_f32_16x16x32_bf16 v[20:23], v[96:99], v[128:131], v[20:23]
	v_mfma_f32_16x16x32_bf16 v[16:19], v[78:81], v[128:131], v[16:19]
	v_mfma_f32_16x16x32_bf16 v[12:15], v[120:123], v[124:127], v[12:15]
	v_mfma_f32_16x16x32_bf16 v[8:11], v[100:103], v[124:127], v[8:11]
	v_mfma_f32_16x16x32_bf16 v[4:7], v[96:99], v[124:127], v[4:7]
	v_mfma_f32_16x16x32_bf16 v[0:3], v[78:81], v[124:127], v[0:3]
	s_setprio 0
	ds_read_b128 v[78:81], v91 offset:16384
	ds_read_b128 v[96:99], v91 offset:18432
	ds_read_b128 v[100:103], v91 offset:20480
	ds_read_b128 v[120:123], v91 offset:22528
	ds_read_b128 v[124:127], v92 offset:49152
	ds_read_b128 v[128:131], v92 offset:51200
	ds_read_b128 v[132:135], v92 offset:53248
	ds_read_b128 v[136:139], v92 offset:55296
	s_setprio 1
	s_waitcnt lgkmcnt(3)
	v_mfma_f32_16x16x32_bf16 v[60:63], v[124:127], v[78:81], v[60:63]
	s_waitcnt lgkmcnt(2)
	v_mfma_f32_16x16x32_bf16 v[56:59], v[128:131], v[78:81], v[56:59]
	s_waitcnt lgkmcnt(1)
	v_mfma_f32_16x16x32_bf16 v[52:55], v[132:135], v[78:81], v[52:55]
	s_waitcnt lgkmcnt(0)
	v_mfma_f32_16x16x32_bf16 v[48:51], v[136:139], v[78:81], v[48:51]
	v_mfma_f32_16x16x32_bf16 v[44:47], v[124:127], v[96:99], v[44:47]
	v_mfma_f32_16x16x32_bf16 v[40:43], v[128:131], v[96:99], v[40:43]
	v_mfma_f32_16x16x32_bf16 v[36:39], v[132:135], v[96:99], v[36:39]
	v_mfma_f32_16x16x32_bf16 v[32:35], v[136:139], v[96:99], v[32:35]
	v_mfma_f32_16x16x32_bf16 v[28:31], v[124:127], v[100:103], v[28:31]
	v_mfma_f32_16x16x32_bf16 v[24:27], v[128:131], v[100:103], v[24:27]
	v_mfma_f32_16x16x32_bf16 v[20:23], v[132:135], v[100:103], v[20:23]
	v_mfma_f32_16x16x32_bf16 v[16:19], v[136:139], v[100:103], v[16:19]
	v_mfma_f32_16x16x32_bf16 v[12:15], v[124:127], v[120:123], v[12:15]
	v_mfma_f32_16x16x32_bf16 v[8:11], v[128:131], v[120:123], v[8:11]
	v_mfma_f32_16x16x32_bf16 v[4:7], v[132:135], v[120:123], v[4:7]
	v_mfma_f32_16x16x32_bf16 v[0:3], v[136:139], v[120:123], v[0:3]
	s_setprio 0
	s_waitcnt vmcnt(0)
	s_cmp_lt_i32 s10, 32
	s_mov_b64 s[0:1], -1
	s_barrier
	s_cbranch_scc1 .LBB0_594
	s_cmp_eq_u32 s10, 32
	s_cselect_b64 s[0:1], -1, 0
	s_and_b64 vcc, exec, s[0:1]
	v_mov_b32_e32 v79, v63
	v_mov_b32_e32 v82, v62
	v_mov_b32_e32 v83, v61
	v_mov_b32_e32 v95, v60
	s_cbranch_vccz .LBB0_323
	v_cmp_nlt_f32_e64 s[8:9], |v60|, s33
	s_and_saveexec_b64 s[12:13], s[8:9]
	s_xor_b64 s[8:9], exec, s[12:13]
	s_cbranch_execz .LBB0_308
	v_add_f32_e64 v78, |v60|, |v60|
	v_mul_f32_e32 v79, 0x3fb8aa3b, v78
	v_rndne_f32_e32 v80, v79
	s_mov_b32 s11, 0x3fb8aa3b
	v_sub_f32_e32 v81, v79, v80
	v_fma_f32 v79, v78, s11, -v79
	v_fmac_f32_e32 v79, 0x32a5705f, v78
	v_add_f32_e32 v79, v81, v79
	v_cvt_i32_f32_e32 v80, v80
	v_exp_f32_e32 v79, v79
	s_mov_b32 s11, 0xc2ce8ed0
	v_cmp_ngt_f32_e32 vcc, s11, v78
	s_mov_b32 s11, 0x42b17218
	v_ldexp_f32 v79, v79, v80
	v_cndmask_b32_e32 v79, 0, v79, vcc
	v_cmp_nlt_f32_e32 vcc, s11, v78
	s_nop 1
	v_cndmask_b32_e32 v78, v112, v79, vcc
	v_add_f32_e32 v78, 1.0, v78
	v_rcp_f32_e32 v78, v78
	s_nop 0
	v_fma_f32 v78, v78, -2.0, 1.0

.LBB0_881:
	s_and_b32 s0, s12, 7
	v_readlane_b32 s8, v180, 8
	s_mul_i32 s0, s0, s8
	s_ashr_i32 s1, s12, 3
	s_add_i32 s0, s0, s1
	s_ashr_i32 s1, s0, 31
	s_lshr_b32 s1, s1, 26
	s_add_i32 s1, s0, s1
	s_ashr_i32 s6, s1, 6
	s_lshl_b32 s6, s6, 3
	s_sub_i32 s8, s8, s6
	s_min_i32 s8, s8, 8
	s_abs_i32 s9, s8
	v_cvt_f32_u32_e32 v0, s9
	s_sub_i32 s11, 0, s9
	s_andn2_b32 s1, s1, 63
	s_sub_i32 s0, s0, s1
	v_rcp_iflag_f32_e32 v0, v0
	s_abs_i32 s1, s0
	s_xor_b32 s10, s0, s8
	s_ashr_i32 s10, s10, 31
	v_mul_f32_e32 v0, 0x4f7ffffe, v0
	v_cvt_u32_f32_e32 v0, v0
	v_add_u32_e32 v6, 0x1000, v68
	s_mov_b64 s[22:23], 0x10000
	s_mov_b64 s[36:37], 0x30000
	v_readfirstlane_b32 s13, v0
	s_mul_i32 s11, s11, s13
	s_mul_hi_u32 s11, s13, s11
	s_add_i32 s13, s13, s11
	s_mul_hi_u32 s11, s1, s13
	s_mul_i32 s13, s11, s9
	s_sub_i32 s1, s1, s13
	s_add_i32 s18, s11, 1
	s_sub_i32 s13, s1, s9
	s_cmp_ge_u32 s1, s9
	s_cselect_b32 s11, s18, s11
	s_cselect_b32 s1, s13, s1
	s_add_i32 s13, s11, 1
	s_cmp_ge_u32 s1, s9
	s_cselect_b32 s1, s13, s11
	s_xor_b32 s1, s1, s10
	s_sub_i32 s9, s1, s10
	s_mul_i32 s1, s9, s8
	s_sub_i32 s0, s0, s1
	s_add_i32 s1, s6, s0
	s_lshl_b32 s24, s1, 7
	s_ashr_i32 s25, s24, 31
	s_lshl_b32 s20, s9, 7
	s_lshl_b64 s[8:9], s[24:25], 11
	v_readfirstlane_b32 s0, v68
	v_lshl_add_u64 v[0:1], v[72:73], 0, s[8:9]
	s_mov_b32 m0, s0
	v_readfirstlane_b32 s0, v6
	v_add_u32_e32 v6, 0x2000, v68
	global_load_lds_dwordx4 v[0:1], off
	v_lshl_add_u64 v[4:5], v[0:1], 0, s[22:23]
	s_mov_b32 m0, s0
	v_readfirstlane_b32 s0, v6
	global_load_lds_dwordx4 v[4:5], off
	v_lshl_add_u64 v[4:5], v[0:1], 0, s[28:29]
	s_mov_b32 m0, s0
	v_lshl_add_u64 v[0:1], v[0:1], 0, s[36:37]
	global_load_lds_dwordx4 v[4:5], off
	v_add_u32_e32 v4, 0x3000, v68
	s_ashr_i32 s21, s20, 31
	v_readfirstlane_b32 s0, v4
	s_mov_b32 m0, s0
	s_lshl_b64 s[10:11], s[20:21], 11
	global_load_lds_dwordx4 v[0:1], off
	v_add_u32_e32 v0, 0x8000, v68
	v_add_u32_e32 v4, 0x9000, v68
	v_readfirstlane_b32 s0, v0
	v_lshl_add_u64 v[2:3], v[74:75], 0, s[10:11]
	s_mov_b32 m0, s0
	v_readfirstlane_b32 s0, v4
	v_add_u32_e32 v4, 0xa000, v68
	global_load_lds_dwordx4 v[2:3], off
	v_lshl_add_u64 v[0:1], v[2:3], 0, s[22:23]
	s_mov_b32 m0, s0
	v_readfirstlane_b32 s0, v4
	global_load_lds_dwordx4 v[0:1], off
	v_lshl_add_u64 v[0:1], v[2:3], 0, s[28:29]
	s_mov_b32 m0, s0
	v_lshl_add_u64 v[86:87], v[84:85], 0, s[8:9]
	global_load_lds_dwordx4 v[0:1], off
	v_lshl_add_u64 v[0:1], v[2:3], 0, s[36:37]
	v_add_u32_e32 v2, 0xb000, v68
	v_lshl_add_u64 v[88:89], v[84:85], 0, s[10:11]
	v_readfirstlane_b32 s0, v2
	s_mov_b32 m0, s0
	s_mov_b32 s0, 0
	global_load_lds_dwordx4 v[0:1], off
	s_waitcnt vmcnt(0)
	v_mov_b32_e32 v0, 0
	s_mov_b64 s[36:37], 0
	v_mov_b32_e32 v1, v0
	v_mov_b32_e32 v2, v0
	v_mov_b32_e32 v3, v0
	v_mov_b32_e32 v4, v0
	v_mov_b32_e32 v5, v0
	v_mov_b32_e32 v6, v0
	v_mov_b32_e32 v7, v0
	v_mov_b32_e32 v8, v0
	v_mov_b32_e32 v9, v0
	v_mov_b32_e32 v10, v0
	v_mov_b32_e32 v11, v0
	v_mov_b32_e32 v12, v0
	v_mov_b32_e32 v13, v0
	v_mov_b32_e32 v14, v0
	v_mov_b32_e32 v15, v0
	v_mov_b32_e32 v16, v0
	v_mov_b32_e32 v17, v0
	v_mov_b32_e32 v18, v0
	v_mov_b32_e32 v19, v0
	v_mov_b32_e32 v20, v0
	v_mov_b32_e32 v21, v0
	v_mov_b32_e32 v22, v0
	v_mov_b32_e32 v23, v0
	v_mov_b32_e32 v24, v0
	v_mov_b32_e32 v25, v0
	v_mov_b32_e32 v26, v0
	v_mov_b32_e32 v27, v0
	v_mov_b32_e32 v28, v0
	v_mov_b32_e32 v29, v0
	v_mov_b32_e32 v30, v0
	v_mov_b32_e32 v31, v0
	v_mov_b32_e32 v32, v0
	v_mov_b32_e32 v33, v0
	v_mov_b32_e32 v34, v0
	v_mov_b32_e32 v35, v0
	v_mov_b32_e32 v36, v0
	v_mov_b32_e32 v37, v0
	v_mov_b32_e32 v38, v0
	v_mov_b32_e32 v39, v0
	v_mov_b32_e32 v40, v0
	v_mov_b32_e32 v41, v0
	v_mov_b32_e32 v42, v0
	v_mov_b32_e32 v43, v0
	v_mov_b32_e32 v44, v0
	v_mov_b32_e32 v45, v0
	v_mov_b32_e32 v46, v0
	v_mov_b32_e32 v47, v0
	v_mov_b32_e32 v48, v0
	v_mov_b32_e32 v49, v0
	v_mov_b32_e32 v50, v0
	v_mov_b32_e32 v51, v0
	v_mov_b32_e32 v52, v0
	v_mov_b32_e32 v53, v0
	v_mov_b32_e32 v54, v0
	v_mov_b32_e32 v55, v0
	v_mov_b32_e32 v56, v0
	v_mov_b32_e32 v57, v0
	v_mov_b32_e32 v58, v0
	v_mov_b32_e32 v59, v0
	v_mov_b32_e32 v60, v0
	v_mov_b32_e32 v61, v0
	v_mov_b32_e32 v62, v0
	v_mov_b32_e32 v63, v0
	v_lshl_add_u64 v[98:99], v[86:87], 0, s[36:37]
	s_mov_b64 s[8:9], 0x1bb00080
	v_lshl_add_u64 v[100:101], v[98:99], 0, s[8:9]
	s_mov_b64 s[8:9], 0x1bb10080
	v_mov_b32_e32 v184, v100
	v_mov_b32_e32 v185, v101
	v_lshl_add_u64 v[100:101], v[98:99], 0, s[8:9]
	s_mov_b64 s[8:9], 0x1bb20080
	v_mov_b32_e32 v186, v100
	v_mov_b32_e32 v187, v101
	v_lshl_add_u64 v[100:101], v[98:99], 0, s[8:9]
	s_mov_b64 s[8:9], 0x1bb30080
	v_mov_b32_e32 v188, v100
	v_mov_b32_e32 v189, v101
	v_lshl_add_u64 v[98:99], v[98:99], 0, s[8:9]
	s_mov_b64 s[8:9], 0x3940080
	v_mov_b32_e32 v190, v98
	v_mov_b32_e32 v191, v99
	v_lshl_add_u64 v[98:99], v[88:89], 0, s[36:37]
	v_lshl_add_u64 v[100:101], v[98:99], 0, s[8:9]
	s_mov_b64 s[8:9], 0x3950080
	v_mov_b32_e32 v192, v100
	v_mov_b32_e32 v193, v101
	v_lshl_add_u64 v[100:101], v[98:99], 0, s[8:9]
	s_mov_b64 s[8:9], 0x3960080
	v_mov_b32_e32 v194, v100
	v_mov_b32_e32 v195, v101
	v_lshl_add_u64 v[100:101], v[98:99], 0, s[8:9]
	s_mov_b64 s[8:9], 0x3970080
	v_mov_b32_e32 v196, v100
	v_mov_b32_e32 v197, v101
	v_lshl_add_u64 v[98:99], v[98:99], 0, s[8:9]
	v_mov_b32_e32 v198, v98
	v_mov_b32_e32 v199, v99
	v_readfirstlane_b32 s100, v68
	s_mov_b64 vcc, 0x80
	s_waitcnt vmcnt(0) lgkmcnt(0)
	s_barrier
.LBB0_882:
	s_and_b32 s6, s0, 0x2000
	s_xor_b32 s8, s6, 0x2000
	s_lshl_b32 s101, s8, 1
	s_add_u32 s101, s101, s100
	s_add_u32 m0, s101, 0x0
	s_nop 0
	global_load_lds_dwordx4 v[184:185], off
	s_add_u32 m0, s101, 0x1000
	v_lshl_add_u64 v[184:185], v[184:185], 0, vcc
	global_load_lds_dwordx4 v[186:187], off
	s_add_u32 m0, s101, 0x2000
	v_lshl_add_u64 v[186:187], v[186:187], 0, vcc
	global_load_lds_dwordx4 v[188:189], off
	s_add_u32 m0, s101, 0x3000
	v_lshl_add_u64 v[188:189], v[188:189], 0, vcc
	global_load_lds_dwordx4 v[190:191], off
	s_add_u32 m0, s101, 0x8000
	v_lshl_add_u64 v[190:191], v[190:191], 0, vcc
	global_load_lds_dwordx4 v[192:193], off
	s_add_u32 m0, s101, 0x9000
	v_lshl_add_u64 v[192:193], v[192:193], 0, vcc
	global_load_lds_dwordx4 v[194:195], off
	s_add_u32 m0, s101, 0xa000
	v_lshl_add_u64 v[194:195], v[194:195], 0, vcc
	global_load_lds_dwordx4 v[196:197], off
	s_add_u32 m0, s101, 0xb000
	v_lshl_add_u64 v[196:197], v[196:197], 0, vcc
	global_load_lds_dwordx4 v[198:199], off
	v_lshl_add_u64 v[198:199], v[198:199], 0, vcc
	s_lshl_b32 s6, s6, 1
	v_add_u32_e32 v102, s6, v90
	v_add_u32_e32 v103, s6, v71
	v_add_u32_e32 v128, v102, v96
	v_add_u32_e32 v144, v103, v96
	ds_read_b128 v[98:101], v128
	ds_read_b128 v[120:123], v128 offset:2048
	ds_read_b128 v[124:127], v128 offset:4096
	ds_read_b128 v[128:131], v128 offset:6144
	ds_read_b128 v[132:135], v144 offset:32768
	ds_read_b128 v[136:139], v144 offset:34816
	ds_read_b128 v[140:143], v144 offset:36864
	ds_read_b128 v[144:147], v144 offset:38912
	s_setprio 1
	s_waitcnt lgkmcnt(0)
	v_mfma_f32_16x16x32_bf16 v[60:63], v[132:135], v[98:101], v[60:63]
	v_mfma_f32_16x16x32_bf16 v[56:59], v[136:139], v[98:101], v[56:59]
	v_mfma_f32_16x16x32_bf16 v[52:55], v[140:143], v[98:101], v[52:55]
	v_mfma_f32_16x16x32_bf16 v[48:51], v[144:147], v[98:101], v[48:51]
	v_mfma_f32_16x16x32_bf16 v[44:47], v[132:135], v[120:123], v[44:47]
	v_mfma_f32_16x16x32_bf16 v[40:43], v[136:139], v[120:123], v[40:43]
	v_mfma_f32_16x16x32_bf16 v[36:39], v[140:143], v[120:123], v[36:39]
	v_mfma_f32_16x16x32_bf16 v[32:35], v[144:147], v[120:123], v[32:35]
	v_mfma_f32_16x16x32_bf16 v[28:31], v[132:135], v[124:127], v[28:31]
	v_mfma_f32_16x16x32_bf16 v[24:27], v[136:139], v[124:127], v[24:27]
	v_mfma_f32_16x16x32_bf16 v[20:23], v[140:143], v[124:127], v[20:23]
	v_mfma_f32_16x16x32_bf16 v[16:19], v[144:147], v[124:127], v[16:19]
	v_mfma_f32_16x16x32_bf16 v[12:15], v[132:135], v[128:131], v[12:15]
	v_mfma_f32_16x16x32_bf16 v[8:11], v[136:139], v[128:131], v[8:11]
	v_mfma_f32_16x16x32_bf16 v[4:7], v[140:143], v[128:131], v[4:7]
	v_mfma_f32_16x16x32_bf16 v[0:3], v[144:147], v[128:131], v[0:3]
	s_setprio 0
	v_add_u32_e32 v102, v102, v97
	ds_read_b128 v[98:101], v102
	ds_read_b128 v[120:123], v102 offset:2048
	ds_read_b128 v[124:127], v102 offset:4096
	ds_read_b128 v[128:131], v102 offset:6144
	v_add_u32_e32 v102, v103, v97
	ds_read_b128 v[132:135], v102 offset:32768
	ds_read_b128 v[136:139], v102 offset:34816
	ds_read_b128 v[140:143], v102 offset:36864
	ds_read_b128 v[144:147], v102 offset:38912
	s_setprio 1
	s_waitcnt lgkmcnt(0)
	v_mfma_f32_16x16x32_bf16 v[60:63], v[132:135], v[98:101], v[60:63]
	v_mfma_f32_16x16x32_bf16 v[56:59], v[136:139], v[98:101], v[56:59]
	v_mfma_f32_16x16x32_bf16 v[52:55], v[140:143], v[98:101], v[52:55]
	v_mfma_f32_16x16x32_bf16 v[48:51], v[144:147], v[98:101], v[48:51]
	v_mfma_f32_16x16x32_bf16 v[44:47], v[132:135], v[120:123], v[44:47]
	v_mfma_f32_16x16x32_bf16 v[40:43], v[136:139], v[120:123], v[40:43]
	v_mfma_f32_16x16x32_bf16 v[36:39], v[140:143], v[120:123], v[36:39]
	v_mfma_f32_16x16x32_bf16 v[32:35], v[144:147], v[120:123], v[32:35]
	v_mfma_f32_16x16x32_bf16 v[28:31], v[132:135], v[124:127], v[28:31]
	v_mfma_f32_16x16x32_bf16 v[24:27], v[136:139], v[124:127], v[24:27]
	v_mfma_f32_16x16x32_bf16 v[20:23], v[140:143], v[124:127], v[20:23]
	v_mfma_f32_16x16x32_bf16 v[16:19], v[144:147], v[124:127], v[16:19]
	v_mfma_f32_16x16x32_bf16 v[12:15], v[132:135], v[128:131], v[12:15]
	v_mfma_f32_16x16x32_bf16 v[8:11], v[136:139], v[128:131], v[8:11]
	v_mfma_f32_16x16x32_bf16 v[4:7], v[140:143], v[128:131], v[4:7]
	v_mfma_f32_16x16x32_bf16 v[0:3], v[144:147], v[128:131], v[0:3]
	s_setprio 0
	s_waitcnt vmcnt(0)
	s_add_u32 s36, s36, 0x80
	s_addc_u32 s37, s37, 0
	s_addk_i32 s0, 0x2000
	s_cmpk_lg_i32 s36, 0x780
	s_waitcnt vmcnt(0)
	s_barrier
	s_cbranch_scc1 .LBB0_882
	ds_read_b128 v[86:89], v92 offset:16384
	ds_read_b128 v[98:101], v92 offset:18432
	ds_read_b128 v[120:123], v92 offset:20480
	ds_read_b128 v[124:127], v92 offset:22528
	ds_read_b128 v[128:131], v93 offset:49152
	ds_read_b128 v[132:135], v93 offset:51200
	ds_read_b128 v[136:139], v93 offset:53248
	ds_read_b128 v[140:143], v93 offset:55296
	s_setprio 1
	s_waitcnt lgkmcnt(3)
	v_mfma_f32_16x16x32_bf16 v[60:63], v[128:131], v[86:89], v[60:63]
	s_waitcnt lgkmcnt(2)
	v_mfma_f32_16x16x32_bf16 v[56:59], v[132:135], v[86:89], v[56:59]
	s_waitcnt lgkmcnt(1)
	v_mfma_f32_16x16x32_bf16 v[52:55], v[136:139], v[86:89], v[52:55]
	s_waitcnt lgkmcnt(0)
	v_mfma_f32_16x16x32_bf16 v[48:51], v[140:143], v[86:89], v[48:51]
	v_mfma_f32_16x16x32_bf16 v[40:43], v[132:135], v[98:101], v[40:43]
	v_mfma_f32_16x16x32_bf16 v[36:39], v[136:139], v[98:101], v[36:39]
	v_mfma_f32_16x16x32_bf16 v[32:35], v[140:143], v[98:101], v[32:35]
	v_mfma_f32_16x16x32_bf16 v[20:23], v[136:139], v[120:123], v[20:23]
	v_mfma_f32_16x16x32_bf16 v[16:19], v[140:143], v[120:123], v[16:19]
	v_mfma_f32_16x16x32_bf16 v[0:3], v[140:143], v[124:127], v[0:3]
	v_mfma_f32_16x16x32_bf16 v[86:89], v[128:131], v[98:101], v[44:47]
	v_mfma_f32_16x16x32_bf16 v[98:101], v[128:131], v[120:123], v[28:31]
	v_mfma_f32_16x16x32_bf16 v[144:147], v[132:135], v[120:123], v[24:27]
	v_mfma_f32_16x16x32_bf16 v[120:123], v[128:131], v[124:127], v[12:15]
	v_mfma_f32_16x16x32_bf16 v[128:131], v[132:135], v[124:127], v[8:11]
	v_mfma_f32_16x16x32_bf16 v[132:135], v[136:139], v[124:127], v[4:7]
	s_setprio 0
	s_nop 1
	ds_read_b128 v[4:7], v94 offset:16384
	ds_read_b128 v[8:11], v94 offset:18432
	ds_read_b128 v[124:127], v94 offset:20480
	ds_read_b128 v[136:139], v94 offset:22528
	ds_read_b128 v[140:143], v95 offset:49152
	ds_read_b128 v[148:151], v95 offset:51200
	ds_read_b128 v[152:155], v95 offset:53248
	ds_read_b128 v[156:159], v95 offset:55296
	s_setprio 1
	s_waitcnt lgkmcnt(3)
	v_mfma_f32_16x16x32_bf16 v[60:63], v[140:143], v[4:7], v[60:63]
	s_waitcnt lgkmcnt(2)
	v_mfma_f32_16x16x32_bf16 v[44:47], v[148:151], v[4:7], v[56:59]
	s_waitcnt lgkmcnt(1)
	v_mfma_f32_16x16x32_bf16 v[28:31], v[152:155], v[4:7], v[52:55]
	s_waitcnt lgkmcnt(0)
	v_mfma_f32_16x16x32_bf16 v[12:15], v[156:159], v[4:7], v[48:51]
	v_mfma_f32_16x16x32_bf16 v[56:59], v[140:143], v[8:11], v[86:89]
	v_mfma_f32_16x16x32_bf16 v[40:43], v[148:151], v[8:11], v[40:43]
	v_mfma_f32_16x16x32_bf16 v[24:27], v[152:155], v[8:11], v[36:39]
	v_mfma_f32_16x16x32_bf16 v[8:11], v[156:159], v[8:11], v[32:35]
	v_mfma_f32_16x16x32_bf16 v[52:55], v[140:143], v[124:127], v[98:101]
	v_mfma_f32_16x16x32_bf16 v[36:39], v[148:151], v[124:127], v[144:147]
	v_mfma_f32_16x16x32_bf16 v[20:23], v[152:155], v[124:127], v[20:23]
	v_mfma_f32_16x16x32_bf16 v[4:7], v[156:159], v[124:127], v[16:19]
	v_mfma_f32_16x16x32_bf16 v[48:51], v[140:143], v[136:139], v[120:123]
	v_mfma_f32_16x16x32_bf16 v[32:35], v[148:151], v[136:139], v[128:131]
	v_mfma_f32_16x16x32_bf16 v[16:19], v[152:155], v[136:139], v[132:135]
	v_mfma_f32_16x16x32_bf16 v[0:3], v[156:159], v[136:139], v[0:3]
	s_setprio 0
	s_waitcnt vmcnt(0)
	s_cmpk_gt_i32 s1, 0x7f
	s_barrier
	s_cbranch_scc0 .LBB0_885
	s_add_i32 s0, s24, 0xffffc000
	s_lshr_b32 s0, s0, 8
	v_readlane_b32 s6, v180, 24
	s_add_i32 s6, s0, s6
	s_and_b32 s10, s24, 0x80
	s_lshl_b64 s[8:9], s[6:7], 8
	v_readlane_b32 s36, v182, 19
	s_or_b32 s8, s8, s10
	s_mov_b64 s[10:11], 0
	v_readlane_b32 s37, v182, 20
	s_branch .LBB0_886

.LBB0_894:
	s_and_b32 s0, s6, 7
	s_mulk_i32 s0, 0x318
	s_ashr_i32 s1, s6, 3
	s_add_i32 s0, s0, s1
	s_mul_hi_i32 s1, s0, 0x2aaaaaab
	s_lshr_b32 s8, s1, 31
	s_ashr_i32 s1, s1, 6
	s_add_i32 s1, s1, s8
	s_lshl_b32 s9, s1, 3
	s_sub_i32 s8, 0x84, s9
	s_min_u32 s10, s8, 8
	v_cvt_f32_ubyte0_e32 v0, s10
	v_rcp_iflag_f32_e32 v0, v0
	s_sub_i32 s11, 0, s10
	s_mulk_i32 s1, 0xfe80
	s_add_i32 s1, s1, s0
	v_mul_f32_e32 v0, 0x4f7ffffe, v0
	v_cvt_u32_f32_e32 v0, v0
	s_abs_i32 s8, s1
	s_ashr_i32 s0, s1, 31
	v_add_u32_e32 v4, 0x1000, v71
	v_readfirstlane_b32 s12, v0
	s_mul_i32 s11, s11, s12
	s_mul_hi_u32 s11, s12, s11
	s_add_i32 s12, s12, s11
	s_mul_hi_u32 s11, s8, s12
	s_mul_i32 s12, s11, s10
	s_sub_i32 s8, s8, s12
	s_add_i32 s12, s11, 1
	s_sub_i32 s13, s8, s10
	s_cmp_ge_u32 s8, s10
	s_cselect_b32 s11, s12, s11
	s_cselect_b32 s8, s13, s8
	s_add_i32 s12, s11, 1
	s_cmp_ge_u32 s8, s10
	s_cselect_b32 s8, s12, s11
	s_xor_b32 s8, s8, s0
	s_sub_i32 s8, s8, s0
	s_mul_i32 s0, s8, s10
	s_sub_i32 s0, s1, s0
	s_add_i32 s9, s0, s9
	s_lshl_b32 s20, s9, 7
	s_ashr_i32 s21, s20, 31
	s_lshl_b64 s[0:1], s[20:21], 11
	v_readfirstlane_b32 s10, v71
	v_lshl_add_u64 v[0:1], v[72:73], 0, s[0:1]
	s_mov_b32 m0, s10
	s_mov_b64 s[12:13], 0x10000
	v_readfirstlane_b32 s10, v4
	v_add_u32_e32 v4, 0x2000, v71
	global_load_lds_dwordx4 v[0:1], off
	v_lshl_add_u64 v[2:3], v[0:1], 0, s[12:13]
	s_mov_b32 m0, s10
	v_readfirstlane_b32 s10, v4
	global_load_lds_dwordx4 v[2:3], off
	v_lshl_add_u64 v[2:3], v[0:1], 0, s[28:29]
	s_mov_b32 m0, s10
	s_lshl_b32 s24, s8, 7
	global_load_lds_dwordx4 v[2:3], off
	v_add_u32_e32 v2, 0x3000, v71
	s_ashr_i32 s25, s24, 31
	s_mov_b64 s[22:23], 0x30000
	v_readfirstlane_b32 s10, v2
	v_add_u32_e32 v2, 0x8000, v71
	s_lshl_b64 s[38:39], s[24:25], 11
	v_lshl_add_u64 v[0:1], v[0:1], 0, s[22:23]
	s_mov_b32 m0, s10
	v_readfirstlane_b32 s10, v2
	v_add_u32_e32 v4, 0x9000, v71
	global_load_lds_dwordx4 v[0:1], off
	v_lshl_add_u64 v[0:1], v[74:75], 0, s[38:39]
	s_mov_b32 m0, s10
	v_readfirstlane_b32 s10, v4
	v_add_u32_e32 v4, 0xa000, v71
	global_load_lds_dwordx4 v[0:1], off
	v_lshl_add_u64 v[2:3], v[0:1], 0, s[12:13]
	s_mov_b32 m0, s10
	v_readfirstlane_b32 s10, v4
	global_load_lds_dwordx4 v[2:3], off
	v_lshl_add_u64 v[2:3], v[0:1], 0, s[28:29]
	s_mov_b32 m0, s10
	v_lshl_add_u64 v[0:1], v[0:1], 0, s[22:23]
	global_load_lds_dwordx4 v[2:3], off
	v_add_u32_e32 v2, 0xb000, v71
	s_mov_b64 s[36:37], 0
	v_readfirstlane_b32 s10, v2
	s_mov_b32 m0, s10
	s_mov_b32 s10, 0
	global_load_lds_dwordx4 v[0:1], off
	s_waitcnt vmcnt(0)
	v_mov_b32_e32 v0, 0
	v_mov_b32_e32 v1, v0
	v_mov_b32_e32 v2, v0
	v_mov_b32_e32 v3, v0
	v_mov_b32_e32 v4, v0
	v_mov_b32_e32 v5, v0
	v_mov_b32_e32 v6, v0
	v_mov_b32_e32 v7, v0
	v_mov_b32_e32 v8, v0
	v_mov_b32_e32 v9, v0
	v_mov_b32_e32 v10, v0
	v_mov_b32_e32 v11, v0
	v_mov_b32_e32 v12, v0
	v_mov_b32_e32 v13, v0
	v_mov_b32_e32 v14, v0
	v_mov_b32_e32 v15, v0
	v_mov_b32_e32 v16, v0
	v_mov_b32_e32 v17, v0
	v_mov_b32_e32 v18, v0
	v_mov_b32_e32 v19, v0
	v_mov_b32_e32 v20, v0
	v_mov_b32_e32 v21, v0
	v_mov_b32_e32 v22, v0
	v_mov_b32_e32 v23, v0
	v_mov_b32_e32 v24, v0
	v_mov_b32_e32 v25, v0
	v_mov_b32_e32 v26, v0
	v_mov_b32_e32 v27, v0
	v_mov_b32_e32 v28, v0
	v_mov_b32_e32 v29, v0
	v_mov_b32_e32 v30, v0
	v_mov_b32_e32 v31, v0
	v_mov_b32_e32 v32, v0
	v_mov_b32_e32 v33, v0
	v_mov_b32_e32 v34, v0
	v_mov_b32_e32 v35, v0
	v_mov_b32_e32 v36, v0
	v_mov_b32_e32 v37, v0
	v_mov_b32_e32 v38, v0
	v_mov_b32_e32 v39, v0
	v_mov_b32_e32 v40, v0
	v_mov_b32_e32 v41, v0
	v_mov_b32_e32 v42, v0
	v_mov_b32_e32 v43, v0
	v_mov_b32_e32 v44, v0
	v_mov_b32_e32 v45, v0
	v_mov_b32_e32 v46, v0
	v_mov_b32_e32 v47, v0
	v_mov_b32_e32 v48, v0
	v_mov_b32_e32 v49, v0
	v_mov_b32_e32 v50, v0
	v_mov_b32_e32 v51, v0
	v_mov_b32_e32 v52, v0
	v_mov_b32_e32 v53, v0
	v_mov_b32_e32 v54, v0
	v_mov_b32_e32 v55, v0
	v_mov_b32_e32 v56, v0
	v_mov_b32_e32 v57, v0
	v_mov_b32_e32 v58, v0
	v_mov_b32_e32 v59, v0
	v_mov_b32_e32 v60, v0
	v_mov_b32_e32 v61, v0
	v_mov_b32_e32 v62, v0
	v_mov_b32_e32 v63, v0
	v_lshl_add_u64 v[82:83], v[78:79], 0, s[0:1]
	v_lshl_add_u64 v[84:85], v[80:81], 0, s[38:39]
	v_lshl_add_u64 v[86:87], v[82:83], 0, s[36:37]
	v_lshl_add_u64 v[88:89], v[86:87], 0, s[76:77]
	v_mov_b32_e32 v184, v88
	v_mov_b32_e32 v185, v89
	v_lshl_add_u64 v[88:89], v[86:87], 0, s[80:81]
	v_mov_b32_e32 v186, v88
	v_mov_b32_e32 v187, v89
	v_lshl_add_u64 v[88:89], v[86:87], 0, s[78:79]
	v_lshl_add_u64 v[86:87], v[86:87], 0, s[88:89]
	v_mov_b32_e32 v188, v88
	v_mov_b32_e32 v189, v89
	v_mov_b32_e32 v190, v86
	v_mov_b32_e32 v191, v87
	v_lshl_add_u64 v[86:87], v[84:85], 0, s[36:37]
	v_lshl_add_u64 v[88:89], v[86:87], 0, s[92:93]
	v_mov_b32_e32 v192, v88
	v_mov_b32_e32 v193, v89
	v_lshl_add_u64 v[88:89], v[86:87], 0, s[96:97]
	v_mov_b32_e32 v194, v88
	v_mov_b32_e32 v195, v89
	v_lshl_add_u64 v[88:89], v[86:87], 0, s[30:31]
	v_mov_b32_e32 v196, v88
	v_mov_b32_e32 v197, v89
	v_lshl_add_u64 v[86:87], v[86:87], 0, s[14:15]
	v_mov_b32_e32 v198, v86
	v_mov_b32_e32 v199, v87
	v_readfirstlane_b32 s100, v71
	s_mov_b64 vcc, 0x80
	s_waitcnt vmcnt(0) lgkmcnt(0)
	s_barrier
.LBB0_895:
	s_and_b32 s0, s10, 0x2000
	s_xor_b32 s1, s0, 0x2000
	s_lshl_b32 s101, s1, 1
	s_add_u32 s101, s101, s100
	s_add_u32 m0, s101, 0x0
	s_nop 0
	global_load_lds_dwordx4 v[184:185], off
	s_add_u32 m0, s101, 0x1000
	v_lshl_add_u64 v[184:185], v[184:185], 0, vcc
	global_load_lds_dwordx4 v[186:187], off
	s_add_u32 m0, s101, 0x2000
	v_lshl_add_u64 v[186:187], v[186:187], 0, vcc
	global_load_lds_dwordx4 v[188:189], off
	s_add_u32 m0, s101, 0x3000
	v_lshl_add_u64 v[188:189], v[188:189], 0, vcc
	global_load_lds_dwordx4 v[190:191], off
	s_add_u32 m0, s101, 0x8000
	v_lshl_add_u64 v[190:191], v[190:191], 0, vcc
	global_load_lds_dwordx4 v[192:193], off
	s_add_u32 m0, s101, 0x9000
	v_lshl_add_u64 v[192:193], v[192:193], 0, vcc
	global_load_lds_dwordx4 v[194:195], off
	s_add_u32 m0, s101, 0xa000
	v_lshl_add_u64 v[194:195], v[194:195], 0, vcc
	global_load_lds_dwordx4 v[196:197], off
	s_add_u32 m0, s101, 0xb000
	v_lshl_add_u64 v[196:197], v[196:197], 0, vcc
	global_load_lds_dwordx4 v[198:199], off
	v_lshl_add_u64 v[198:199], v[198:199], 0, vcc
	s_lshl_b32 s0, s0, 1
	v_add_u32_e32 v68, s0, v120
	v_add_u32_e32 v102, s0, v121
	v_add_u32_e32 v98, v68, v133
	v_add_u32_e32 v103, v102, v133
	ds_read_b128 v[86:89], v98
	ds_read_b128 v[90:93], v98 offset:2048
	ds_read_b128 v[94:97], v98 offset:4096
	ds_read_b128 v[98:101], v98 offset:6144
	ds_read_b128 v[144:147], v103 offset:32768
	ds_read_b128 v[148:151], v103 offset:34816
	ds_read_b128 v[152:155], v103 offset:36864
	ds_read_b128 v[156:159], v103 offset:38912
	s_setprio 1
	s_waitcnt lgkmcnt(0)
	v_mfma_f32_16x16x32_bf16 v[60:63], v[86:89], v[144:147], v[60:63]
	v_mfma_f32_16x16x32_bf16 v[56:59], v[86:89], v[148:151], v[56:59]
	v_mfma_f32_16x16x32_bf16 v[52:55], v[86:89], v[152:155], v[52:55]
	v_mfma_f32_16x16x32_bf16 v[48:51], v[86:89], v[156:159], v[48:51]
	v_mfma_f32_16x16x32_bf16 v[44:47], v[90:93], v[144:147], v[44:47]
	v_mfma_f32_16x16x32_bf16 v[40:43], v[90:93], v[148:151], v[40:43]
	v_mfma_f32_16x16x32_bf16 v[36:39], v[90:93], v[152:155], v[36:39]
	v_mfma_f32_16x16x32_bf16 v[32:35], v[90:93], v[156:159], v[32:35]
	v_mfma_f32_16x16x32_bf16 v[28:31], v[94:97], v[144:147], v[28:31]
	v_mfma_f32_16x16x32_bf16 v[24:27], v[94:97], v[148:151], v[24:27]
	v_mfma_f32_16x16x32_bf16 v[20:23], v[94:97], v[152:155], v[20:23]
	v_mfma_f32_16x16x32_bf16 v[16:19], v[94:97], v[156:159], v[16:19]
	v_mfma_f32_16x16x32_bf16 v[12:15], v[98:101], v[144:147], v[12:15]
	v_mfma_f32_16x16x32_bf16 v[8:11], v[98:101], v[148:151], v[8:11]
	v_mfma_f32_16x16x32_bf16 v[4:7], v[98:101], v[152:155], v[4:7]
	v_mfma_f32_16x16x32_bf16 v[0:3], v[98:101], v[156:159], v[0:3]
	s_setprio 0
	v_add_u32_e32 v68, v68, v134
	ds_read_b128 v[86:89], v68
	ds_read_b128 v[90:93], v68 offset:2048
	ds_read_b128 v[94:97], v68 offset:4096
	ds_read_b128 v[98:101], v68 offset:6144
	v_add_u32_e32 v68, v102, v134
	ds_read_b128 v[144:147], v68 offset:32768
	ds_read_b128 v[148:151], v68 offset:34816
	ds_read_b128 v[152:155], v68 offset:36864
	ds_read_b128 v[156:159], v68 offset:38912
	s_setprio 1
	s_waitcnt lgkmcnt(0)
	v_mfma_f32_16x16x32_bf16 v[60:63], v[86:89], v[144:147], v[60:63]
	v_mfma_f32_16x16x32_bf16 v[56:59], v[86:89], v[148:151], v[56:59]
	v_mfma_f32_16x16x32_bf16 v[52:55], v[86:89], v[152:155], v[52:55]
	v_mfma_f32_16x16x32_bf16 v[48:51], v[86:89], v[156:159], v[48:51]
	v_mfma_f32_16x16x32_bf16 v[44:47], v[90:93], v[144:147], v[44:47]
	v_mfma_f32_16x16x32_bf16 v[40:43], v[90:93], v[148:151], v[40:43]
	v_mfma_f32_16x16x32_bf16 v[36:39], v[90:93], v[152:155], v[36:39]
	v_mfma_f32_16x16x32_bf16 v[32:35], v[90:93], v[156:159], v[32:35]
	v_mfma_f32_16x16x32_bf16 v[28:31], v[94:97], v[144:147], v[28:31]
	v_mfma_f32_16x16x32_bf16 v[24:27], v[94:97], v[148:151], v[24:27]
	v_mfma_f32_16x16x32_bf16 v[20:23], v[94:97], v[152:155], v[20:23]
	v_mfma_f32_16x16x32_bf16 v[16:19], v[94:97], v[156:159], v[16:19]
	v_mfma_f32_16x16x32_bf16 v[12:15], v[98:101], v[144:147], v[12:15]
	v_mfma_f32_16x16x32_bf16 v[8:11], v[98:101], v[148:151], v[8:11]
	v_mfma_f32_16x16x32_bf16 v[4:7], v[98:101], v[152:155], v[4:7]
	v_mfma_f32_16x16x32_bf16 v[0:3], v[98:101], v[156:159], v[0:3]
	s_setprio 0
	s_addk_i32 s10, 0x2000
	s_waitcnt vmcnt(0)
	s_add_u32 s36, s36, 0x80
	s_addc_u32 s37, s37, 0
	s_cmpk_lg_i32 s36, 0x780
	s_waitcnt vmcnt(0)
	s_barrier
	s_cbranch_scc1 .LBB0_895
	ds_read_b128 v[82:85], v122 offset:55296
	ds_read_b128 v[86:89], v122 offset:53248
	ds_read_b128 v[90:93], v122 offset:51200
	ds_read_b128 v[94:97], v122 offset:49152
	ds_read_b128 v[98:101], v123 offset:22528
	ds_read_b128 v[144:147], v123 offset:20480
	ds_read_b128 v[148:151], v123 offset:18432
	ds_read_b128 v[152:155], v123 offset:16384
	s_setprio 1
	s_waitcnt lgkmcnt(0)
	v_mfma_f32_16x16x32_bf16 v[60:63], v[152:155], v[94:97], v[60:63]
	v_mfma_f32_16x16x32_bf16 v[52:55], v[152:155], v[86:89], v[52:55]
	v_mfma_f32_16x16x32_bf16 v[48:51], v[152:155], v[82:85], v[48:51]
	v_mfma_f32_16x16x32_bf16 v[44:47], v[148:151], v[94:97], v[44:47]
	v_mfma_f32_16x16x32_bf16 v[40:43], v[148:151], v[90:93], v[40:43]
	v_mfma_f32_16x16x32_bf16 v[36:39], v[148:151], v[86:89], v[36:39]
	v_mfma_f32_16x16x32_bf16 v[32:35], v[148:151], v[82:85], v[32:35]
	v_mfma_f32_16x16x32_bf16 v[4:7], v[98:101], v[86:89], v[4:7]
	v_mfma_f32_16x16x32_bf16 v[156:159], v[152:155], v[90:93], v[56:59]
	v_mfma_f32_16x16x32_bf16 v[148:151], v[144:147], v[94:97], v[28:31]
	v_mfma_f32_16x16x32_bf16 v[152:155], v[144:147], v[90:93], v[24:27]
	v_mfma_f32_16x16x32_bf16 v[160:163], v[144:147], v[86:89], v[20:23]
	v_mfma_f32_16x16x32_bf16 v[144:147], v[144:147], v[82:85], v[16:19]
	v_mfma_f32_16x16x32_bf16 v[94:97], v[98:101], v[94:97], v[12:15]
	v_mfma_f32_16x16x32_bf16 v[90:93], v[98:101], v[90:93], v[8:11]
	v_mfma_f32_16x16x32_bf16 v[82:85], v[98:101], v[82:85], v[0:3]
	s_setprio 0
	s_nop 1
	ds_read_b128 v[0:3], v124 offset:16384
	ds_read_b128 v[8:11], v124 offset:18432
	ds_read_b128 v[12:15], v124 offset:20480
	ds_read_b128 v[86:89], v124 offset:22528
	ds_read_b128 v[98:101], v125 offset:49152
	ds_read_b128 v[164:167], v125 offset:51200
	ds_read_b128 v[168:171], v125 offset:53248
	ds_read_b128 v[172:175], v125 offset:55296
	s_setprio 1
	s_waitcnt lgkmcnt(3)
	v_mfma_f32_16x16x32_bf16 v[56:59], v[0:3], v[98:101], v[60:63]
	s_waitcnt lgkmcnt(2)
	v_mfma_f32_16x16x32_bf16 v[60:63], v[0:3], v[164:167], v[156:159]
	s_waitcnt lgkmcnt(1)
	v_mfma_f32_16x16x32_bf16 v[24:27], v[0:3], v[168:171], v[52:55]
	s_waitcnt lgkmcnt(0)
	v_mfma_f32_16x16x32_bf16 v[28:31], v[0:3], v[172:175], v[48:51]
	v_mfma_f32_16x16x32_bf16 v[52:55], v[8:11], v[98:101], v[44:47]
	v_mfma_f32_16x16x32_bf16 v[48:51], v[8:11], v[164:167], v[40:43]
	v_mfma_f32_16x16x32_bf16 v[16:19], v[8:11], v[168:171], v[36:39]
	v_mfma_f32_16x16x32_bf16 v[20:23], v[8:11], v[172:175], v[32:35]
	v_mfma_f32_16x16x32_bf16 v[40:43], v[12:15], v[98:101], v[148:151]
	v_mfma_f32_16x16x32_bf16 v[44:47], v[12:15], v[164:167], v[152:155]
	v_mfma_f32_16x16x32_bf16 v[8:11], v[12:15], v[168:171], v[160:163]
	v_mfma_f32_16x16x32_bf16 v[12:15], v[12:15], v[172:175], v[144:147]
	v_mfma_f32_16x16x32_bf16 v[32:35], v[86:89], v[98:101], v[94:97]
	v_mfma_f32_16x16x32_bf16 v[36:39], v[86:89], v[164:167], v[90:93]
	v_mfma_f32_16x16x32_bf16 v[0:3], v[86:89], v[168:171], v[4:7]
	v_mfma_f32_16x16x32_bf16 v[4:7], v[86:89], v[172:175], v[82:85]
	s_setprio 0
	s_waitcnt vmcnt(0)
	s_cmpk_lt_i32 s9, 0x80
	s_cselect_b64 s[42:43], -1, 0
	s_cmpk_gt_i32 s9, 0x7f
	s_mov_b64 s[0:1], -1
	s_barrier
	s_cbranch_scc0 .LBB0_904
	s_and_b32 s10, s20, 0x80
	s_cbranch_execz .LBB0_905

.LBB0_1238:
	s_bfe_u32 s11, s9, 0x20008
	s_lshl_b32 s10, s18, 6
	s_lshl_b32 s9, s11, 9
	s_and_b32 s10, s10, 0x180
	s_or_b32 s9, s9, s10
	s_and_b32 s19, s12, 0x300
	s_mul_i32 s9, s9, 0x8400
	v_readlane_b32 s20, v181, 46
	v_readlane_b32 s21, v181, 47
	s_add_u32 s20, s20, s9
	s_addc_u32 s21, s21, 0
	s_ashr_i32 s9, s8, 31
	s_lshl_b64 s[8:9], s[8:9], 1
	s_add_u32 s20, s20, s8
	s_addc_u32 s21, s21, s9
	s_and_b64 s[0:1], s[0:1], exec
	s_cselect_b32 s23, s91, s73
	s_cselect_b32 s22, s90, s72
	s_lshl_b32 s0, s18, 7
	s_lshl_b32 s1, s11, 8
	s_and_b32 s0, s0, 0x80
	s_or_b32 s1, s1, s0
	s_mul_i32 s1, s1, 0x8400
	s_add_u32 s1, s22, s1
	s_addc_u32 s37, s23, 0
	s_add_u32 s38, s1, s8
	v_lshl_add_u64 v[0:1], s[20:21], 0, v[76:77]
	v_readfirstlane_b32 s1, v82
	v_add_u32_e32 v6, 0x1000, v82
	s_addc_u32 s39, s37, s9
	v_lshl_add_u64 v[0:1], v[0:1], 0, v[68:69]
	s_mov_b32 m0, s1
	s_mov_b64 s[20:21], 0x108000
	v_readfirstlane_b32 s1, v6
	v_add_u32_e32 v6, 0x2000, v82
	v_lshl_add_u64 v[2:3], s[38:39], 0, v[76:77]
	global_load_lds_dwordx4 v[0:1], off
	v_lshl_add_u64 v[4:5], v[0:1], 0, s[20:21]
	s_mov_b32 m0, s1
	s_mov_b64 s[38:39], 0x210000
	v_readfirstlane_b32 s1, v6
	global_load_lds_dwordx4 v[4:5], off
	v_lshl_add_u64 v[4:5], v[0:1], 0, s[38:39]
	s_mov_b32 m0, s1
	s_mov_b64 s[40:41], 0x318000
	global_load_lds_dwordx4 v[4:5], off
	v_add_u32_e32 v4, 0x3000, v82
	v_lshl_add_u64 v[0:1], v[0:1], 0, s[40:41]
	v_readfirstlane_b32 s1, v4
	s_mov_b32 m0, s1
	v_add_u32_e32 v4, 0x9000, v82
	global_load_lds_dwordx4 v[0:1], off
	v_add_u32_e32 v0, 0x8000, v82
	v_lshl_add_u64 v[2:3], v[2:3], 0, v[68:69]
	v_readfirstlane_b32 s1, v0
	s_mov_b32 m0, s1
	v_readfirstlane_b32 s1, v4
	v_add_u32_e32 v4, 0xa000, v82
	global_load_lds_dwordx4 v[2:3], off
	v_lshl_add_u64 v[0:1], v[2:3], 0, s[20:21]
	s_mov_b32 m0, s1
	v_readfirstlane_b32 s1, v4
	global_load_lds_dwordx4 v[0:1], off
	v_lshl_add_u64 v[0:1], v[2:3], 0, s[38:39]
	s_mov_b32 m0, s1
	s_add_i32 s19, s18, s19
	global_load_lds_dwordx4 v[0:1], off
	v_lshl_add_u64 v[0:1], v[2:3], 0, s[40:41]
	v_add_u32_e32 v2, 0xb000, v82
	s_bfe_u32 s20, s19, 0x20008
	v_readfirstlane_b32 s1, v2
	s_mov_b32 m0, s1
	s_bfe_u32 s18, s18, 0x20001
	global_load_lds_dwordx4 v[0:1], off
	s_mul_i32 s19, s20, 0x840000
	s_mul_i32 s18, s18, 0x210000
	s_lshl_b32 s1, s36, 7
	s_add_i32 s19, s19, s18
	s_add_u32 s1, s1, 0x80
	s_lshl_b32 s18, s19, 1
	s_add_u32 s18, s8, s18
	s_addc_u32 s19, s9, 0
	v_lshl_add_u64 v[78:79], v[74:75], 0, s[18:19]
	s_bfe_u32 s19, s6, 0x10003
	s_mul_i32 s18, s20, 0x420000
	s_mul_i32 s19, s19, 0x210000
	s_add_i32 s18, s18, s19
	s_lshl_b32 s18, s18, 1
	s_add_u32 s8, s8, s18
	s_waitcnt vmcnt(0)
	v_lshl_add_u64 v[0:1], s[22:23], 0, v[72:73]
	s_addc_u32 s9, s9, 0
	v_lshl_add_u64 v[80:81], v[0:1], 0, s[8:9]
	v_mov_b32_e32 v0, 0
	s_mov_b64 s[20:21], 0
	s_mov_b32 s8, 0
	v_mov_b32_e32 v1, v0
	v_mov_b32_e32 v2, v0
	v_mov_b32_e32 v3, v0
	v_mov_b32_e32 v4, v0
	v_mov_b32_e32 v5, v0
	v_mov_b32_e32 v6, v0
	v_mov_b32_e32 v7, v0
	v_mov_b32_e32 v8, v0
	v_mov_b32_e32 v9, v0
	v_mov_b32_e32 v10, v0
	v_mov_b32_e32 v11, v0
	v_mov_b32_e32 v12, v0
	v_mov_b32_e32 v13, v0
	v_mov_b32_e32 v14, v0
	v_mov_b32_e32 v15, v0
	v_mov_b32_e32 v16, v0
	v_mov_b32_e32 v17, v0
	v_mov_b32_e32 v18, v0
	v_mov_b32_e32 v19, v0
	v_mov_b32_e32 v20, v0
	v_mov_b32_e32 v21, v0
	v_mov_b32_e32 v22, v0
	v_mov_b32_e32 v23, v0
	v_mov_b32_e32 v24, v0
	v_mov_b32_e32 v25, v0
	v_mov_b32_e32 v26, v0
	v_mov_b32_e32 v27, v0
	v_mov_b32_e32 v28, v0
	v_mov_b32_e32 v29, v0
	v_mov_b32_e32 v30, v0
	v_mov_b32_e32 v31, v0
	v_mov_b32_e32 v32, v0
	v_mov_b32_e32 v33, v0
	v_mov_b32_e32 v34, v0
	v_mov_b32_e32 v35, v0
	v_mov_b32_e32 v36, v0
	v_mov_b32_e32 v37, v0
	v_mov_b32_e32 v38, v0
	v_mov_b32_e32 v39, v0
	v_mov_b32_e32 v40, v0
	v_mov_b32_e32 v41, v0
	v_mov_b32_e32 v42, v0
	v_mov_b32_e32 v43, v0
	v_mov_b32_e32 v44, v0
	v_mov_b32_e32 v45, v0
	v_mov_b32_e32 v46, v0
	v_mov_b32_e32 v47, v0
	v_mov_b32_e32 v48, v0
	v_mov_b32_e32 v49, v0
	v_mov_b32_e32 v50, v0
	v_mov_b32_e32 v51, v0
	v_mov_b32_e32 v52, v0
	v_mov_b32_e32 v53, v0
	v_mov_b32_e32 v54, v0
	v_mov_b32_e32 v55, v0
	v_mov_b32_e32 v56, v0
	v_mov_b32_e32 v57, v0
	v_mov_b32_e32 v58, v0
	v_mov_b32_e32 v59, v0
	v_mov_b32_e32 v60, v0
	v_mov_b32_e32 v61, v0
	v_mov_b32_e32 v62, v0
	v_mov_b32_e32 v63, v0
	v_lshl_add_u64 v[88:89], v[78:79], 0, s[20:21]
	s_mov_b64 s[18:19], 0xd400080
	v_lshl_add_u64 v[90:91], v[88:89], 0, s[18:19]
	s_mov_b64 s[18:19], 0xd508080
	v_mov_b32_e32 v184, v90
	v_mov_b32_e32 v185, v91
	v_lshl_add_u64 v[90:91], v[88:89], 0, s[18:19]
	s_mov_b64 s[18:19], 0xd610080
	v_mov_b32_e32 v186, v90
	v_mov_b32_e32 v187, v91
	v_lshl_add_u64 v[90:91], v[88:89], 0, s[18:19]
	s_mov_b64 s[18:19], 0xd718080
	v_mov_b32_e32 v188, v90
	v_mov_b32_e32 v189, v91
	v_lshl_add_u64 v[88:89], v[88:89], 0, s[18:19]
	v_mov_b32_e32 v190, v88
	v_mov_b32_e32 v191, v89
	v_lshl_add_u64 v[88:89], v[80:81], 0, s[20:21]
	v_lshl_add_u64 v[90:91], v[88:89], 0, s[92:93]
	s_mov_b64 s[18:19], 0x108080
	v_mov_b32_e32 v192, v90
	v_mov_b32_e32 v193, v91
	v_lshl_add_u64 v[90:91], v[88:89], 0, s[18:19]
	s_mov_b64 s[18:19], 0x210080
	v_mov_b32_e32 v194, v90
	v_mov_b32_e32 v195, v91
	v_lshl_add_u64 v[90:91], v[88:89], 0, s[18:19]
	s_mov_b64 s[18:19], 0x318080
	v_mov_b32_e32 v196, v90
	v_mov_b32_e32 v197, v91
	v_lshl_add_u64 v[88:89], v[88:89], 0, s[18:19]
	v_mov_b32_e32 v198, v88
	v_mov_b32_e32 v199, v89
	v_readfirstlane_b32 s100, v82
	s_mov_b64 vcc, 0x80
	s_waitcnt vmcnt(0) lgkmcnt(0)
	s_barrier
.LBB0_1239:
	s_and_b32 s9, s8, 0x2000
	s_xor_b32 s18, s9, 0x2000
	s_lshl_b32 s101, s18, 1
	s_add_u32 s101, s101, s100
	s_add_u32 m0, s101, 0x0
	s_nop 0
	global_load_lds_dwordx4 v[184:185], off
	s_add_u32 m0, s101, 0x1000
	v_lshl_add_u64 v[184:185], v[184:185], 0, vcc
	global_load_lds_dwordx4 v[186:187], off
	s_add_u32 m0, s101, 0x2000
	v_lshl_add_u64 v[186:187], v[186:187], 0, vcc
	global_load_lds_dwordx4 v[188:189], off
	s_add_u32 m0, s101, 0x3000
	v_lshl_add_u64 v[188:189], v[188:189], 0, vcc
	global_load_lds_dwordx4 v[190:191], off
	s_add_u32 m0, s101, 0x8000
	v_lshl_add_u64 v[190:191], v[190:191], 0, vcc
	global_load_lds_dwordx4 v[192:193], off
	s_add_u32 m0, s101, 0x9000
	v_lshl_add_u64 v[192:193], v[192:193], 0, vcc
	global_load_lds_dwordx4 v[194:195], off
	s_add_u32 m0, s101, 0xa000
	v_lshl_add_u64 v[194:195], v[194:195], 0, vcc
	global_load_lds_dwordx4 v[196:197], off
	s_add_u32 m0, s101, 0xb000
	v_lshl_add_u64 v[196:197], v[196:197], 0, vcc
	global_load_lds_dwordx4 v[198:199], off
	v_lshl_add_u64 v[198:199], v[198:199], 0, vcc
	s_lshl_b32 s9, s9, 1
	v_add_u32_e32 v136, s9, v84
	v_add_u32_e32 v137, s9, v83
	v_add_u32_e32 v100, v136, v86
	v_add_u32_e32 v132, v137, v86
	ds_read_b128 v[88:91], v100
	ds_read_b128 v[92:95], v100 offset:2048
	ds_read_b128 v[96:99], v100 offset:4096
	ds_read_b128 v[100:103], v100 offset:6144
	ds_read_b128 v[120:123], v132 offset:32768
	ds_read_b128 v[124:127], v132 offset:34816
	ds_read_b128 v[128:131], v132 offset:36864
	ds_read_b128 v[132:135], v132 offset:38912
	s_setprio 1
	s_waitcnt lgkmcnt(0)
	v_mfma_f32_16x16x32_bf16 v[60:63], v[120:123], v[88:91], v[60:63]
	v_mfma_f32_16x16x32_bf16 v[56:59], v[124:127], v[88:91], v[56:59]
	v_mfma_f32_16x16x32_bf16 v[52:55], v[128:131], v[88:91], v[52:55]
	v_mfma_f32_16x16x32_bf16 v[48:51], v[132:135], v[88:91], v[48:51]
	v_mfma_f32_16x16x32_bf16 v[44:47], v[120:123], v[92:95], v[44:47]
	v_mfma_f32_16x16x32_bf16 v[40:43], v[124:127], v[92:95], v[40:43]
	v_mfma_f32_16x16x32_bf16 v[36:39], v[128:131], v[92:95], v[36:39]
	v_mfma_f32_16x16x32_bf16 v[32:35], v[132:135], v[92:95], v[32:35]
	v_mfma_f32_16x16x32_bf16 v[28:31], v[120:123], v[96:99], v[28:31]
	v_mfma_f32_16x16x32_bf16 v[24:27], v[124:127], v[96:99], v[24:27]
	v_mfma_f32_16x16x32_bf16 v[20:23], v[128:131], v[96:99], v[20:23]
	v_mfma_f32_16x16x32_bf16 v[16:19], v[132:135], v[96:99], v[16:19]
	v_mfma_f32_16x16x32_bf16 v[12:15], v[120:123], v[100:103], v[12:15]
	v_mfma_f32_16x16x32_bf16 v[8:11], v[124:127], v[100:103], v[8:11]
	v_mfma_f32_16x16x32_bf16 v[4:7], v[128:131], v[100:103], v[4:7]
	v_mfma_f32_16x16x32_bf16 v[0:3], v[132:135], v[100:103], v[0:3]
	s_setprio 0
	v_add_u32_e32 v100, v136, v87
	v_add_u32_e32 v132, v137, v87
	ds_read_b128 v[88:91], v100
	ds_read_b128 v[92:95], v100 offset:2048
	ds_read_b128 v[96:99], v100 offset:4096
	ds_read_b128 v[100:103], v100 offset:6144
	ds_read_b128 v[120:123], v132 offset:32768
	ds_read_b128 v[124:127], v132 offset:34816
	ds_read_b128 v[128:131], v132 offset:36864
	ds_read_b128 v[132:135], v132 offset:38912
	s_setprio 1
	s_waitcnt lgkmcnt(0)
	v_mfma_f32_16x16x32_bf16 v[60:63], v[120:123], v[88:91], v[60:63]
	v_mfma_f32_16x16x32_bf16 v[56:59], v[124:127], v[88:91], v[56:59]
	v_mfma_f32_16x16x32_bf16 v[52:55], v[128:131], v[88:91], v[52:55]
	v_mfma_f32_16x16x32_bf16 v[48:51], v[132:135], v[88:91], v[48:51]
	v_mfma_f32_16x16x32_bf16 v[44:47], v[120:123], v[92:95], v[44:47]
	v_mfma_f32_16x16x32_bf16 v[40:43], v[124:127], v[92:95], v[40:43]
	v_mfma_f32_16x16x32_bf16 v[36:39], v[128:131], v[92:95], v[36:39]
	v_mfma_f32_16x16x32_bf16 v[32:35], v[132:135], v[92:95], v[32:35]
	v_mfma_f32_16x16x32_bf16 v[28:31], v[120:123], v[96:99], v[28:31]
	v_mfma_f32_16x16x32_bf16 v[24:27], v[124:127], v[96:99], v[24:27]
	v_mfma_f32_16x16x32_bf16 v[20:23], v[128:131], v[96:99], v[20:23]
	v_mfma_f32_16x16x32_bf16 v[16:19], v[132:135], v[96:99], v[16:19]
	v_mfma_f32_16x16x32_bf16 v[12:15], v[120:123], v[100:103], v[12:15]
	v_mfma_f32_16x16x32_bf16 v[8:11], v[124:127], v[100:103], v[8:11]
	v_mfma_f32_16x16x32_bf16 v[4:7], v[128:131], v[100:103], v[4:7]
	v_mfma_f32_16x16x32_bf16 v[0:3], v[132:135], v[100:103], v[0:3]
	s_setprio 0
	s_waitcnt vmcnt(0)
	s_add_u32 s20, s20, 0x80
	s_addc_u32 s21, s21, 0
	s_addk_i32 s8, 0x2000
	s_cmp_lg_u32 s1, s20
	s_waitcnt vmcnt(0)
	s_barrier
	s_cbranch_scc1 .LBB0_1239
	s_lshl_b32 s1, s36, 14
	s_addk_i32 s1, 0x4000
	s_and_b32 s1, s1, 0x4000
	v_add_u32_e32 v132, s1, v84
	v_add_u32_e32 v133, s1, v83
	v_add_u32_e32 v96, v132, v86
	v_add_u32_e32 v128, v133, v86
	ds_read_b128 v[78:81], v96
	ds_read_b128 v[88:91], v96 offset:2048
	ds_read_b128 v[92:95], v96 offset:4096
	ds_read_b128 v[96:99], v96 offset:6144
	ds_read_b128 v[100:103], v128 offset:32768
	ds_read_b128 v[120:123], v128 offset:34816
	ds_read_b128 v[124:127], v128 offset:36864
	ds_read_b128 v[128:131], v128 offset:38912
	s_setprio 1
	s_waitcnt lgkmcnt(3)
	v_mfma_f32_16x16x32_bf16 v[60:63], v[100:103], v[78:81], v[60:63]
	s_waitcnt lgkmcnt(2)
	v_mfma_f32_16x16x32_bf16 v[56:59], v[120:123], v[78:81], v[56:59]
	s_waitcnt lgkmcnt(1)
	v_mfma_f32_16x16x32_bf16 v[52:55], v[124:127], v[78:81], v[52:55]
	s_waitcnt lgkmcnt(0)
	v_mfma_f32_16x16x32_bf16 v[48:51], v[128:131], v[78:81], v[48:51]
	v_mfma_f32_16x16x32_bf16 v[44:47], v[100:103], v[88:91], v[44:47]
	v_mfma_f32_16x16x32_bf16 v[40:43], v[120:123], v[88:91], v[40:43]
	v_mfma_f32_16x16x32_bf16 v[36:39], v[124:127], v[88:91], v[36:39]
	v_mfma_f32_16x16x32_bf16 v[32:35], v[128:131], v[88:91], v[32:35]
	v_mfma_f32_16x16x32_bf16 v[28:31], v[100:103], v[92:95], v[28:31]
	v_mfma_f32_16x16x32_bf16 v[24:27], v[120:123], v[92:95], v[24:27]
	v_mfma_f32_16x16x32_bf16 v[20:23], v[124:127], v[92:95], v[20:23]
	v_mfma_f32_16x16x32_bf16 v[16:19], v[128:131], v[92:95], v[16:19]
	v_mfma_f32_16x16x32_bf16 v[12:15], v[100:103], v[96:99], v[12:15]
	v_mfma_f32_16x16x32_bf16 v[8:11], v[120:123], v[96:99], v[8:11]
	v_mfma_f32_16x16x32_bf16 v[4:7], v[124:127], v[96:99], v[4:7]
	v_mfma_f32_16x16x32_bf16 v[0:3], v[128:131], v[96:99], v[0:3]
	s_setprio 0
	v_add_u32_e32 v96, v132, v87
	v_add_u32_e32 v128, v133, v87
	ds_read_b128 v[78:81], v96
	ds_read_b128 v[88:91], v96 offset:2048
	ds_read_b128 v[92:95], v96 offset:4096
	ds_read_b128 v[96:99], v96 offset:6144
	ds_read_b128 v[100:103], v128 offset:32768
	ds_read_b128 v[120:123], v128 offset:34816
	ds_read_b128 v[124:127], v128 offset:36864
	ds_read_b128 v[128:131], v128 offset:38912
	s_setprio 1
	s_waitcnt lgkmcnt(3)
	v_mfma_f32_16x16x32_bf16 v[60:63], v[100:103], v[78:81], v[60:63]
	s_waitcnt lgkmcnt(2)
	v_mfma_f32_16x16x32_bf16 v[56:59], v[120:123], v[78:81], v[56:59]
	s_waitcnt lgkmcnt(1)
	v_mfma_f32_16x16x32_bf16 v[52:55], v[124:127], v[78:81], v[52:55]
	s_waitcnt lgkmcnt(0)
	v_mfma_f32_16x16x32_bf16 v[48:51], v[128:131], v[78:81], v[48:51]
	v_mfma_f32_16x16x32_bf16 v[44:47], v[100:103], v[88:91], v[44:47]
	v_mfma_f32_16x16x32_bf16 v[40:43], v[120:123], v[88:91], v[40:43]
	v_mfma_f32_16x16x32_bf16 v[36:39], v[124:127], v[88:91], v[36:39]
	v_mfma_f32_16x16x32_bf16 v[32:35], v[128:131], v[88:91], v[32:35]
	v_mfma_f32_16x16x32_bf16 v[28:31], v[100:103], v[92:95], v[28:31]
	v_mfma_f32_16x16x32_bf16 v[24:27], v[120:123], v[92:95], v[24:27]
	v_mfma_f32_16x16x32_bf16 v[20:23], v[124:127], v[92:95], v[20:23]
	v_mfma_f32_16x16x32_bf16 v[16:19], v[128:131], v[92:95], v[16:19]
	v_mfma_f32_16x16x32_bf16 v[12:15], v[100:103], v[96:99], v[12:15]
	v_mfma_f32_16x16x32_bf16 v[8:11], v[120:123], v[96:99], v[8:11]
	v_mfma_f32_16x16x32_bf16 v[4:7], v[124:127], v[96:99], v[4:7]
	v_mfma_f32_16x16x32_bf16 v[0:3], v[128:131], v[96:99], v[0:3]
	s_setprio 0
	s_lshl_b32 s1, s25, 3
	s_lshl_b32 s8, s11, 1
	s_or_b32 s1, s8, s1
	s_or_b32 s1, s1, s13
	s_lshl_b32 s1, s1, 4
	s_or_b32 s8, s1, s24
	s_ashr_i32 s9, s8, 31
	s_lshl_b64 s[8:9], s[8:9], 18
	s_add_u32 s8, s52, s8
	v_add_lshl_u32 v78, s10, v71, 8
	s_addc_u32 s9, s53, s9
	v_or_b32_e32 v80, s0, v85
	v_ashrrev_i32_e32 v79, 31, v78
	v_lshl_add_u64 v[78:79], v[78:79], 1, s[8:9]
	v_cvt_pk_bf16_f32 v60, v60, v61
	v_cvt_pk_bf16_f32 v61, v62, v63
	v_lshlrev_b32_e32 v62, 1, v80
	v_mov_b32_e32 v63, v69
	v_lshl_add_u64 v[80:81], v[78:79], 0, v[62:63]
	v_cvt_pk_bf16_f32 v48, v48, v49
	v_cvt_pk_bf16_f32 v49, v50, v51
	s_mov_b64 s[0:1], 0x2000
	s_waitcnt vmcnt(0)
	s_barrier
	global_store_dwordx2 v[80:81], v[48:49], off offset:96
	v_lshl_add_u64 v[48:49], v[78:79], 0, s[0:1]
	v_cvt_pk_bf16_f32 v44, v44, v45
	v_cvt_pk_bf16_f32 v45, v46, v47
	v_lshl_add_u64 v[46:47], v[48:49], 0, v[62:63]
	v_cvt_pk_bf16_f32 v40, v40, v41
	v_cvt_pk_bf16_f32 v41, v42, v43
	v_or_b32_e32 v42, 32, v62
	v_mov_b32_e32 v43, v69
	global_store_dwordx2 v[46:47], v[44:45], off
	v_lshl_add_u64 v[44:45], v[48:49], 0, v[42:43]
	v_cvt_pk_bf16_f32 v36, v36, v37
	v_cvt_pk_bf16_f32 v37, v38, v39
	v_or_b32_e32 v38, 64, v62
	v_mov_b32_e32 v39, v69
	global_store_dwordx2 v[44:45], v[40:41], off
	v_lshl_add_u64 v[40:41], v[48:49], 0, v[38:39]
	v_cvt_pk_bf16_f32 v32, v32, v33
	v_cvt_pk_bf16_f32 v33, v34, v35
	v_or_b32_e32 v34, 0x60, v62
	v_mov_b32_e32 v35, v69
	global_store_dwordx2 v[40:41], v[36:37], off
	v_lshl_add_u64 v[36:37], v[48:49], 0, v[34:35]
	s_mov_b64 s[0:1], 0x4000
	global_store_dwordx2 v[36:37], v[32:33], off
	v_lshl_add_u64 v[32:33], v[78:79], 0, s[0:1]
	v_cvt_pk_bf16_f32 v16, v16, v17
	v_cvt_pk_bf16_f32 v17, v18, v19
	v_lshl_add_u64 v[18:19], v[32:33], 0, v[34:35]
	s_mov_b64 s[0:1], 0x6000
	global_store_dwordx2 v[18:19], v[16:17], off
	v_lshl_add_u64 v[16:17], v[78:79], 0, s[0:1]
	v_readlane_b32 s0, v181, 50
	s_add_i32 s6, s6, s84
	s_add_i32 s12, s12, s0
	v_cvt_pk_bf16_f32 v56, v56, v57
	v_cvt_pk_bf16_f32 v57, v58, v59
	v_cvt_pk_bf16_f32 v52, v52, v53
	v_cvt_pk_bf16_f32 v53, v54, v55
	v_cvt_pk_bf16_f32 v28, v28, v29
	v_cvt_pk_bf16_f32 v29, v30, v31
	v_lshl_add_u64 v[30:31], v[32:33], 0, v[62:63]
	v_cvt_pk_bf16_f32 v24, v24, v25
	v_cvt_pk_bf16_f32 v25, v26, v27
	v_lshl_add_u64 v[26:27], v[32:33], 0, v[42:43]
	v_cvt_pk_bf16_f32 v20, v20, v21
	v_cvt_pk_bf16_f32 v21, v22, v23
	v_lshl_add_u64 v[22:23], v[32:33], 0, v[38:39]
	v_cvt_pk_bf16_f32 v12, v12, v13
	v_cvt_pk_bf16_f32 v13, v14, v15
	v_lshl_add_u64 v[14:15], v[16:17], 0, v[62:63]
	v_cvt_pk_bf16_f32 v8, v8, v9
	v_cvt_pk_bf16_f32 v9, v10, v11
	v_lshl_add_u64 v[10:11], v[16:17], 0, v[42:43]
	v_cvt_pk_bf16_f32 v4, v4, v5
	v_cvt_pk_bf16_f32 v5, v6, v7
	v_lshl_add_u64 v[6:7], v[16:17], 0, v[38:39]
	v_cvt_pk_bf16_f32 v0, v0, v1
	v_cvt_pk_bf16_f32 v1, v2, v3
	v_lshl_add_u64 v[2:3], v[16:17], 0, v[34:35]
	s_cmpk_lt_i32 s6, 0x800
	global_store_dwordx2 v[80:81], v[60:61], off
	global_store_dwordx2 v[80:81], v[56:57], off offset:32
	global_store_dwordx2 v[80:81], v[52:53], off offset:64
	global_store_dwordx2 v[30:31], v[28:29], off
	global_store_dwordx2 v[26:27], v[24:25], off
	global_store_dwordx2 v[22:23], v[20:21], off
	global_store_dwordx2 v[14:15], v[12:13], off
	global_store_dwordx2 v[10:11], v[8:9], off
	global_store_dwordx2 v[6:7], v[4:5], off
	global_store_dwordx2 v[2:3], v[0:1], off
	s_cbranch_scc1 .LBB0_1234
	v_readlane_b32 s50, v180, 0
	s_mov_b32 s18, 0x42ce8ed0
	s_mov_b32 s19, 0xc2b17218
	s_mov_b32 s48, s5
	v_readlane_b32 s51, v180, 1

.LBB0_1486:
	s_and_b32 s0, s12, 7
	v_readlane_b32 s8, v180, 8
	s_mul_i32 s0, s0, s8
	s_ashr_i32 s1, s12, 3
	s_add_i32 s0, s0, s1
	s_ashr_i32 s1, s0, 31
	s_lshr_b32 s1, s1, 26
	s_add_i32 s1, s0, s1
	s_ashr_i32 s6, s1, 6
	s_lshl_b32 s6, s6, 3
	s_sub_i32 s8, s8, s6
	s_min_i32 s8, s8, 8
	s_abs_i32 s9, s8
	v_cvt_f32_u32_e32 v0, s9
	s_sub_i32 s11, 0, s9
	s_andn2_b32 s1, s1, 63
	s_sub_i32 s0, s0, s1
	v_rcp_iflag_f32_e32 v0, v0
	s_abs_i32 s1, s0
	s_xor_b32 s10, s0, s8
	s_ashr_i32 s10, s10, 31
	v_mul_f32_e32 v0, 0x4f7ffffe, v0
	v_cvt_u32_f32_e32 v0, v0
	v_add_u32_e32 v6, 0x1000, v68
	s_mov_b64 s[22:23], 0x40000
	s_mov_b64 s[36:37], 0x60000
	v_readfirstlane_b32 s13, v0
	s_mul_i32 s11, s11, s13
	s_mul_hi_u32 s11, s13, s11
	s_add_i32 s13, s13, s11
	s_mul_hi_u32 s11, s1, s13
	s_mul_i32 s13, s11, s9
	s_sub_i32 s1, s1, s13
	s_add_i32 s18, s11, 1
	s_sub_i32 s13, s1, s9
	s_cmp_ge_u32 s1, s9
	s_cselect_b32 s11, s18, s11
	s_cselect_b32 s1, s13, s1
	s_add_i32 s13, s11, 1
	s_cmp_ge_u32 s1, s9
	s_cselect_b32 s1, s13, s11
	s_xor_b32 s1, s1, s10
	s_sub_i32 s9, s1, s10
	s_mul_i32 s1, s9, s8
	s_sub_i32 s0, s0, s1
	s_add_i32 s1, s6, s0
	s_lshl_b32 s24, s1, 7
	s_ashr_i32 s25, s24, 31
	s_lshl_b32 s20, s9, 7
	s_lshl_b64 s[8:9], s[24:25], 12
	v_readfirstlane_b32 s0, v68
	v_lshl_add_u64 v[0:1], v[72:73], 0, s[8:9]
	s_mov_b32 m0, s0
	v_readfirstlane_b32 s0, v6
	v_add_u32_e32 v6, 0x2000, v68
	global_load_lds_dwordx4 v[0:1], off
	v_lshl_add_u64 v[4:5], v[0:1], 0, s[28:29]
	s_mov_b32 m0, s0
	v_readfirstlane_b32 s0, v6
	global_load_lds_dwordx4 v[4:5], off
	v_lshl_add_u64 v[4:5], v[0:1], 0, s[22:23]
	s_mov_b32 m0, s0
	v_lshl_add_u64 v[0:1], v[0:1], 0, s[36:37]
	global_load_lds_dwordx4 v[4:5], off
	v_add_u32_e32 v4, 0x3000, v68
	s_ashr_i32 s21, s20, 31
	v_readfirstlane_b32 s0, v4
	s_mov_b32 m0, s0
	s_lshl_b64 s[10:11], s[20:21], 12
	global_load_lds_dwordx4 v[0:1], off
	v_add_u32_e32 v0, 0x8000, v68
	v_add_u32_e32 v4, 0x9000, v68
	v_readfirstlane_b32 s0, v0
	v_lshl_add_u64 v[2:3], v[74:75], 0, s[10:11]
	s_mov_b32 m0, s0
	v_readfirstlane_b32 s0, v4
	v_add_u32_e32 v4, 0xa000, v68
	global_load_lds_dwordx4 v[2:3], off
	v_lshl_add_u64 v[0:1], v[2:3], 0, s[28:29]
	s_mov_b32 m0, s0
	v_readfirstlane_b32 s0, v4
	global_load_lds_dwordx4 v[0:1], off
	v_lshl_add_u64 v[0:1], v[2:3], 0, s[22:23]
	s_mov_b32 m0, s0
	v_lshl_add_u64 v[88:89], v[84:85], 0, s[8:9]
	global_load_lds_dwordx4 v[0:1], off
	v_lshl_add_u64 v[0:1], v[2:3], 0, s[36:37]
	v_add_u32_e32 v2, 0xb000, v68
	v_lshl_add_u64 v[90:91], v[86:87], 0, s[10:11]
	v_readfirstlane_b32 s0, v2
	s_mov_b32 m0, s0
	s_mov_b32 s0, 0
	global_load_lds_dwordx4 v[0:1], off
	s_waitcnt vmcnt(0)
	v_mov_b32_e32 v0, 0
	s_mov_b64 s[36:37], 0
	v_mov_b32_e32 v1, v0
	v_mov_b32_e32 v2, v0
	v_mov_b32_e32 v3, v0
	v_mov_b32_e32 v4, v0
	v_mov_b32_e32 v5, v0
	v_mov_b32_e32 v6, v0
	v_mov_b32_e32 v7, v0
	v_mov_b32_e32 v8, v0
	v_mov_b32_e32 v9, v0
	v_mov_b32_e32 v10, v0
	v_mov_b32_e32 v11, v0
	v_mov_b32_e32 v12, v0
	v_mov_b32_e32 v13, v0
	v_mov_b32_e32 v14, v0
	v_mov_b32_e32 v15, v0
	v_mov_b32_e32 v16, v0
	v_mov_b32_e32 v17, v0
	v_mov_b32_e32 v18, v0
	v_mov_b32_e32 v19, v0
	v_mov_b32_e32 v20, v0
	v_mov_b32_e32 v21, v0
	v_mov_b32_e32 v22, v0
	v_mov_b32_e32 v23, v0
	v_mov_b32_e32 v24, v0
	v_mov_b32_e32 v25, v0
	v_mov_b32_e32 v26, v0
	v_mov_b32_e32 v27, v0
	v_mov_b32_e32 v28, v0
	v_mov_b32_e32 v29, v0
	v_mov_b32_e32 v30, v0
	v_mov_b32_e32 v31, v0
	v_mov_b32_e32 v32, v0
	v_mov_b32_e32 v33, v0
	v_mov_b32_e32 v34, v0
	v_mov_b32_e32 v35, v0
	v_mov_b32_e32 v36, v0
	v_mov_b32_e32 v37, v0
	v_mov_b32_e32 v38, v0
	v_mov_b32_e32 v39, v0
	v_mov_b32_e32 v40, v0
	v_mov_b32_e32 v41, v0
	v_mov_b32_e32 v42, v0
	v_mov_b32_e32 v43, v0
	v_mov_b32_e32 v44, v0
	v_mov_b32_e32 v45, v0
	v_mov_b32_e32 v46, v0
	v_mov_b32_e32 v47, v0
	v_mov_b32_e32 v48, v0
	v_mov_b32_e32 v49, v0
	v_mov_b32_e32 v50, v0
	v_mov_b32_e32 v51, v0
	v_mov_b32_e32 v52, v0
	v_mov_b32_e32 v53, v0
	v_mov_b32_e32 v54, v0
	v_mov_b32_e32 v55, v0
	v_mov_b32_e32 v56, v0
	v_mov_b32_e32 v57, v0
	v_mov_b32_e32 v58, v0
	v_mov_b32_e32 v59, v0
	v_mov_b32_e32 v60, v0
	v_mov_b32_e32 v61, v0
	v_mov_b32_e32 v62, v0
	v_mov_b32_e32 v63, v0
	v_lshl_add_u64 v[100:101], v[88:89], 0, s[36:37]
	s_mov_b64 s[8:9], 0x15800080
	v_lshl_add_u64 v[102:103], v[100:101], 0, s[8:9]
	s_mov_b64 s[8:9], 0x15820080
	v_mov_b32_e32 v184, v102
	v_mov_b32_e32 v185, v103
	v_lshl_add_u64 v[102:103], v[100:101], 0, s[8:9]
	s_mov_b64 s[8:9], 0x15840080
	v_mov_b32_e32 v186, v102
	v_mov_b32_e32 v187, v103
	v_lshl_add_u64 v[102:103], v[100:101], 0, s[8:9]
	s_mov_b64 s[8:9], 0x15860080
	v_mov_b32_e32 v188, v102
	v_mov_b32_e32 v189, v103
	v_lshl_add_u64 v[100:101], v[100:101], 0, s[8:9]
	s_mov_b64 s[8:9], 0x1800080
	v_mov_b32_e32 v190, v100
	v_mov_b32_e32 v191, v101
	v_lshl_add_u64 v[100:101], v[90:91], 0, s[36:37]
	v_lshl_add_u64 v[102:103], v[100:101], 0, s[8:9]
	s_mov_b64 s[8:9], 0x1820080
	v_mov_b32_e32 v192, v102
	v_mov_b32_e32 v193, v103
	v_lshl_add_u64 v[102:103], v[100:101], 0, s[8:9]
	s_mov_b64 s[8:9], 0x1840080
	v_mov_b32_e32 v194, v102
	v_mov_b32_e32 v195, v103
	v_lshl_add_u64 v[102:103], v[100:101], 0, s[8:9]
	s_mov_b64 s[8:9], 0x1860080
	v_mov_b32_e32 v196, v102
	v_mov_b32_e32 v197, v103
	v_lshl_add_u64 v[100:101], v[100:101], 0, s[8:9]
	v_mov_b32_e32 v198, v100
	v_mov_b32_e32 v199, v101
	v_readfirstlane_b32 s100, v68
	s_mov_b64 vcc, 0x80
	s_waitcnt vmcnt(0) lgkmcnt(0)
	s_barrier
.LBB0_1487:
	s_and_b32 s6, s0, 0x2000
	s_xor_b32 s8, s6, 0x2000
	s_lshl_b32 s101, s8, 1
	s_add_u32 s101, s101, s100
	s_add_u32 m0, s101, 0x0
	s_nop 0
	global_load_lds_dwordx4 v[184:185], off
	s_add_u32 m0, s101, 0x1000
	v_lshl_add_u64 v[184:185], v[184:185], 0, vcc
	global_load_lds_dwordx4 v[186:187], off
	s_add_u32 m0, s101, 0x2000
	v_lshl_add_u64 v[186:187], v[186:187], 0, vcc
	global_load_lds_dwordx4 v[188:189], off
	s_add_u32 m0, s101, 0x3000
	v_lshl_add_u64 v[188:189], v[188:189], 0, vcc
	global_load_lds_dwordx4 v[190:191], off
	s_add_u32 m0, s101, 0x8000
	v_lshl_add_u64 v[190:191], v[190:191], 0, vcc
	global_load_lds_dwordx4 v[192:193], off
	s_add_u32 m0, s101, 0x9000
	v_lshl_add_u64 v[192:193], v[192:193], 0, vcc
	global_load_lds_dwordx4 v[194:195], off
	s_add_u32 m0, s101, 0xa000
	v_lshl_add_u64 v[194:195], v[194:195], 0, vcc
	global_load_lds_dwordx4 v[196:197], off
	s_add_u32 m0, s101, 0xb000
	v_lshl_add_u64 v[196:197], v[196:197], 0, vcc
	global_load_lds_dwordx4 v[198:199], off
	v_lshl_add_u64 v[198:199], v[198:199], 0, vcc
	s_lshl_b32 s6, s6, 1
	v_add_u32_e32 v148, s6, v92
	v_add_u32_e32 v149, s6, v71
	v_add_u32_e32 v128, v148, v98
	v_add_u32_e32 v144, v149, v98
	ds_read_b128 v[100:103], v128
	ds_read_b128 v[120:123], v128 offset:2048
	ds_read_b128 v[124:127], v128 offset:4096
	ds_read_b128 v[128:131], v128 offset:6144
	ds_read_b128 v[132:135], v144 offset:32768
	ds_read_b128 v[136:139], v144 offset:34816
	ds_read_b128 v[140:143], v144 offset:36864
	ds_read_b128 v[144:147], v144 offset:38912
	s_setprio 1
	s_waitcnt lgkmcnt(0)
	v_mfma_f32_16x16x32_bf16 v[60:63], v[132:135], v[100:103], v[60:63]
	v_mfma_f32_16x16x32_bf16 v[56:59], v[136:139], v[100:103], v[56:59]
	v_mfma_f32_16x16x32_bf16 v[52:55], v[140:143], v[100:103], v[52:55]
	v_mfma_f32_16x16x32_bf16 v[48:51], v[144:147], v[100:103], v[48:51]
	v_mfma_f32_16x16x32_bf16 v[44:47], v[132:135], v[120:123], v[44:47]
	v_mfma_f32_16x16x32_bf16 v[40:43], v[136:139], v[120:123], v[40:43]
	v_mfma_f32_16x16x32_bf16 v[36:39], v[140:143], v[120:123], v[36:39]
	v_mfma_f32_16x16x32_bf16 v[32:35], v[144:147], v[120:123], v[32:35]
	v_mfma_f32_16x16x32_bf16 v[28:31], v[132:135], v[124:127], v[28:31]
	v_mfma_f32_16x16x32_bf16 v[24:27], v[136:139], v[124:127], v[24:27]
	v_mfma_f32_16x16x32_bf16 v[20:23], v[140:143], v[124:127], v[20:23]
	v_mfma_f32_16x16x32_bf16 v[16:19], v[144:147], v[124:127], v[16:19]
	v_mfma_f32_16x16x32_bf16 v[12:15], v[132:135], v[128:131], v[12:15]
	v_mfma_f32_16x16x32_bf16 v[8:11], v[136:139], v[128:131], v[8:11]
	v_mfma_f32_16x16x32_bf16 v[4:7], v[140:143], v[128:131], v[4:7]
	v_mfma_f32_16x16x32_bf16 v[0:3], v[144:147], v[128:131], v[0:3]
	s_setprio 0
	v_add_u32_e32 v128, v148, v99
	v_add_u32_e32 v144, v149, v99
	ds_read_b128 v[100:103], v128
	ds_read_b128 v[120:123], v128 offset:2048
	ds_read_b128 v[124:127], v128 offset:4096
	ds_read_b128 v[128:131], v128 offset:6144
	ds_read_b128 v[132:135], v144 offset:32768
	ds_read_b128 v[136:139], v144 offset:34816
	ds_read_b128 v[140:143], v144 offset:36864
	ds_read_b128 v[144:147], v144 offset:38912
	s_setprio 1
	s_waitcnt lgkmcnt(0)
	v_mfma_f32_16x16x32_bf16 v[60:63], v[132:135], v[100:103], v[60:63]
	v_mfma_f32_16x16x32_bf16 v[56:59], v[136:139], v[100:103], v[56:59]
	v_mfma_f32_16x16x32_bf16 v[52:55], v[140:143], v[100:103], v[52:55]
	v_mfma_f32_16x16x32_bf16 v[48:51], v[144:147], v[100:103], v[48:51]
	v_mfma_f32_16x16x32_bf16 v[44:47], v[132:135], v[120:123], v[44:47]
	v_mfma_f32_16x16x32_bf16 v[40:43], v[136:139], v[120:123], v[40:43]
	v_mfma_f32_16x16x32_bf16 v[36:39], v[140:143], v[120:123], v[36:39]
	v_mfma_f32_16x16x32_bf16 v[32:35], v[144:147], v[120:123], v[32:35]
	v_mfma_f32_16x16x32_bf16 v[28:31], v[132:135], v[124:127], v[28:31]
	v_mfma_f32_16x16x32_bf16 v[24:27], v[136:139], v[124:127], v[24:27]
	v_mfma_f32_16x16x32_bf16 v[20:23], v[140:143], v[124:127], v[20:23]
	v_mfma_f32_16x16x32_bf16 v[16:19], v[144:147], v[124:127], v[16:19]
	v_mfma_f32_16x16x32_bf16 v[12:15], v[132:135], v[128:131], v[12:15]
	v_mfma_f32_16x16x32_bf16 v[8:11], v[136:139], v[128:131], v[8:11]
	v_mfma_f32_16x16x32_bf16 v[4:7], v[140:143], v[128:131], v[4:7]
	v_mfma_f32_16x16x32_bf16 v[0:3], v[144:147], v[128:131], v[0:3]
	s_setprio 0
	s_waitcnt vmcnt(0)
	s_add_u32 s36, s36, 0x80
	s_addc_u32 s37, s37, 0
	s_addk_i32 s0, 0x2000
	s_cmpk_lg_i32 s36, 0xf80
	s_waitcnt vmcnt(0)
	s_barrier
	s_cbranch_scc1 .LBB0_1487
	ds_read_b128 v[88:91], v94 offset:16384
	ds_read_b128 v[100:103], v94 offset:18432
	ds_read_b128 v[120:123], v94 offset:20480
	ds_read_b128 v[124:127], v94 offset:22528
	ds_read_b128 v[128:131], v95 offset:49152
	ds_read_b128 v[132:135], v95 offset:51200
	ds_read_b128 v[136:139], v95 offset:53248
	ds_read_b128 v[140:143], v95 offset:55296
	s_setprio 1
	s_waitcnt lgkmcnt(3)
	v_mfma_f32_16x16x32_bf16 v[60:63], v[128:131], v[88:91], v[60:63]
	s_waitcnt lgkmcnt(2)
	v_mfma_f32_16x16x32_bf16 v[56:59], v[132:135], v[88:91], v[56:59]
	s_waitcnt lgkmcnt(1)
	v_mfma_f32_16x16x32_bf16 v[52:55], v[136:139], v[88:91], v[52:55]
	s_waitcnt lgkmcnt(0)
	v_mfma_f32_16x16x32_bf16 v[48:51], v[140:143], v[88:91], v[48:51]
	v_mfma_f32_16x16x32_bf16 v[40:43], v[132:135], v[100:103], v[40:43]
	v_mfma_f32_16x16x32_bf16 v[36:39], v[136:139], v[100:103], v[36:39]
	v_mfma_f32_16x16x32_bf16 v[32:35], v[140:143], v[100:103], v[32:35]
	v_mfma_f32_16x16x32_bf16 v[20:23], v[136:139], v[120:123], v[20:23]
	v_mfma_f32_16x16x32_bf16 v[16:19], v[140:143], v[120:123], v[16:19]
	v_mfma_f32_16x16x32_bf16 v[0:3], v[140:143], v[124:127], v[0:3]
	v_mfma_f32_16x16x32_bf16 v[88:91], v[128:131], v[100:103], v[44:47]
	v_mfma_f32_16x16x32_bf16 v[100:103], v[128:131], v[120:123], v[28:31]
	v_mfma_f32_16x16x32_bf16 v[144:147], v[132:135], v[120:123], v[24:27]
	v_mfma_f32_16x16x32_bf16 v[120:123], v[128:131], v[124:127], v[12:15]
	v_mfma_f32_16x16x32_bf16 v[128:131], v[132:135], v[124:127], v[8:11]
	v_mfma_f32_16x16x32_bf16 v[132:135], v[136:139], v[124:127], v[4:7]
	s_setprio 0
	s_nop 1
	ds_read_b128 v[4:7], v96 offset:16384
	ds_read_b128 v[8:11], v96 offset:18432
	ds_read_b128 v[124:127], v96 offset:20480
	ds_read_b128 v[136:139], v96 offset:22528
	ds_read_b128 v[140:143], v97 offset:49152
	ds_read_b128 v[148:151], v97 offset:51200
	ds_read_b128 v[152:155], v97 offset:53248
	ds_read_b128 v[156:159], v97 offset:55296
	s_setprio 1
	s_waitcnt lgkmcnt(3)
	v_mfma_f32_16x16x32_bf16 v[60:63], v[140:143], v[4:7], v[60:63]
	s_waitcnt lgkmcnt(2)
	v_mfma_f32_16x16x32_bf16 v[44:47], v[148:151], v[4:7], v[56:59]
	s_waitcnt lgkmcnt(1)
	v_mfma_f32_16x16x32_bf16 v[28:31], v[152:155], v[4:7], v[52:55]
	s_waitcnt lgkmcnt(0)
	v_mfma_f32_16x16x32_bf16 v[12:15], v[156:159], v[4:7], v[48:51]
	v_mfma_f32_16x16x32_bf16 v[56:59], v[140:143], v[8:11], v[88:91]
	v_mfma_f32_16x16x32_bf16 v[40:43], v[148:151], v[8:11], v[40:43]
	v_mfma_f32_16x16x32_bf16 v[24:27], v[152:155], v[8:11], v[36:39]
	v_mfma_f32_16x16x32_bf16 v[8:11], v[156:159], v[8:11], v[32:35]
	v_mfma_f32_16x16x32_bf16 v[52:55], v[140:143], v[124:127], v[100:103]
	v_mfma_f32_16x16x32_bf16 v[36:39], v[148:151], v[124:127], v[144:147]
	v_mfma_f32_16x16x32_bf16 v[20:23], v[152:155], v[124:127], v[20:23]
	v_mfma_f32_16x16x32_bf16 v[4:7], v[156:159], v[124:127], v[16:19]
	v_mfma_f32_16x16x32_bf16 v[48:51], v[140:143], v[136:139], v[120:123]
	v_mfma_f32_16x16x32_bf16 v[32:35], v[148:151], v[136:139], v[128:131]
	v_mfma_f32_16x16x32_bf16 v[16:19], v[152:155], v[136:139], v[132:135]
	v_mfma_f32_16x16x32_bf16 v[0:3], v[156:159], v[136:139], v[0:3]
	s_setprio 0
	s_waitcnt vmcnt(0)
	s_cmpk_gt_i32 s1, 0x7f
	s_barrier
	s_cbranch_scc0 .LBB0_1490
	s_add_i32 s0, s24, 0xffffc000
	s_lshr_b32 s0, s0, 8
	v_readlane_b32 s6, v180, 24
	s_add_i32 s6, s0, s6
	s_and_b32 s10, s24, 0x80
	s_lshl_b64 s[8:9], s[6:7], 8
	v_readlane_b32 s36, v182, 19
	s_or_b32 s8, s8, s10
	s_mov_b64 s[10:11], 0
	v_readlane_b32 s37, v182, 20
	s_branch .LBB0_1491

.LBB0_1497:
	s_and_b32 s1, s0, 7
	s_mulk_i32 s1, 0x318
	s_ashr_i32 s6, s0, 3
	s_add_i32 s1, s1, s6
	s_mul_hi_i32 s6, s1, 0x2aaaaaab
	s_lshr_b32 s8, s6, 31
	s_ashr_i32 s6, s6, 6
	s_add_i32 s6, s6, s8
	s_lshl_b32 s8, s6, 3
	s_sub_i32 s9, 0x84, s8
	s_min_u32 s9, s9, 8
	v_cvt_f32_ubyte0_e32 v0, s9
	v_rcp_iflag_f32_e32 v0, v0
	s_sub_i32 s11, 0, s9
	s_mulk_i32 s6, 0xfe80
	s_add_i32 s6, s6, s1
	v_mul_f32_e32 v0, 0x4f7ffffe, v0
	v_cvt_u32_f32_e32 v0, v0
	s_abs_i32 s10, s6
	s_ashr_i32 s1, s6, 31
	v_add_u32_e32 v6, 0x1000, v82
	v_readfirstlane_b32 s12, v0
	s_mul_i32 s11, s11, s12
	s_mul_hi_u32 s11, s12, s11
	s_add_i32 s12, s12, s11
	s_mul_hi_u32 s11, s10, s12
	s_mul_i32 s12, s11, s9
	s_sub_i32 s10, s10, s12
	s_add_i32 s12, s11, 1
	s_sub_i32 s13, s10, s9
	s_cmp_ge_u32 s10, s9
	s_cselect_b32 s11, s12, s11
	s_cselect_b32 s10, s13, s10
	s_add_i32 s12, s11, 1
	s_cmp_ge_u32 s10, s9
	s_cselect_b32 s10, s12, s11
	s_xor_b32 s10, s10, s1
	s_sub_i32 s1, s10, s1
	s_mul_i32 s9, s1, s9
	s_sub_i32 s6, s6, s9
	s_add_i32 s8, s8, s6
	s_lshl_b32 s20, s8, 7
	s_ashr_i32 s21, s20, 31
	s_lshl_b64 s[8:9], s[20:21], 11
	v_readfirstlane_b32 s6, v82
	v_lshl_add_u64 v[0:1], v[72:73], 0, s[8:9]
	s_mov_b32 m0, s6
	s_mov_b64 s[12:13], 0x10000
	v_readfirstlane_b32 s6, v6
	v_add_u32_e32 v6, 0x2000, v82
	global_load_lds_dwordx4 v[0:1], off
	v_lshl_add_u64 v[4:5], v[0:1], 0, s[12:13]
	s_mov_b32 m0, s6
	v_readfirstlane_b32 s6, v6
	global_load_lds_dwordx4 v[4:5], off
	v_lshl_add_u64 v[4:5], v[0:1], 0, s[28:29]
	s_mov_b32 m0, s6
	s_mov_b64 s[36:37], 0x30000
	global_load_lds_dwordx4 v[4:5], off
	v_add_u32_e32 v4, 0x3000, v82
	s_lshl_b32 s24, s1, 7
	v_readfirstlane_b32 s6, v4
	v_lshl_add_u64 v[0:1], v[0:1], 0, s[36:37]
	s_mov_b32 m0, s6
	s_ashr_i32 s25, s24, 31
	global_load_lds_dwordx4 v[0:1], off
	v_add_u32_e32 v0, 0x8000, v82
	s_lshl_b64 s[10:11], s[24:25], 11
	v_readfirstlane_b32 s6, v0
	v_add_u32_e32 v4, 0x9000, v82
	v_lshl_add_u64 v[2:3], v[74:75], 0, s[10:11]
	s_mov_b32 m0, s6
	v_readfirstlane_b32 s6, v4
	v_add_u32_e32 v4, 0xa000, v82
	global_load_lds_dwordx4 v[2:3], off
	v_lshl_add_u64 v[0:1], v[2:3], 0, s[12:13]
	s_mov_b32 m0, s6
	v_readfirstlane_b32 s6, v4
	global_load_lds_dwordx4 v[0:1], off
	v_lshl_add_u64 v[0:1], v[2:3], 0, s[28:29]
	s_mov_b32 m0, s6
	v_lshl_add_u64 v[78:79], v[76:77], 0, s[8:9]
	global_load_lds_dwordx4 v[0:1], off
	v_lshl_add_u64 v[0:1], v[2:3], 0, s[36:37]
	v_add_u32_e32 v2, 0xb000, v82
	v_lshl_add_u64 v[80:81], v[76:77], 0, s[10:11]
	v_readfirstlane_b32 s6, v2
	s_mov_b32 m0, s6
	s_mov_b32 s6, 0
	global_load_lds_dwordx4 v[0:1], off
	s_waitcnt vmcnt(0)
	v_mov_b32_e32 v0, 0
	s_mov_b64 s[36:37], 0
	v_mov_b32_e32 v1, v0
	v_mov_b32_e32 v2, v0
	v_mov_b32_e32 v3, v0
	v_mov_b32_e32 v4, v0
	v_mov_b32_e32 v5, v0
	v_mov_b32_e32 v6, v0
	v_mov_b32_e32 v7, v0
	v_mov_b32_e32 v8, v0
	v_mov_b32_e32 v9, v0
	v_mov_b32_e32 v10, v0
	v_mov_b32_e32 v11, v0
	v_mov_b32_e32 v12, v0
	v_mov_b32_e32 v13, v0
	v_mov_b32_e32 v14, v0
	v_mov_b32_e32 v15, v0
	v_mov_b32_e32 v16, v0
	v_mov_b32_e32 v17, v0
	v_mov_b32_e32 v18, v0
	v_mov_b32_e32 v19, v0
	v_mov_b32_e32 v20, v0
	v_mov_b32_e32 v21, v0
	v_mov_b32_e32 v22, v0
	v_mov_b32_e32 v23, v0
	v_mov_b32_e32 v24, v0
	v_mov_b32_e32 v25, v0
	v_mov_b32_e32 v26, v0
	v_mov_b32_e32 v27, v0
	v_mov_b32_e32 v28, v0
	v_mov_b32_e32 v29, v0
	v_mov_b32_e32 v30, v0
	v_mov_b32_e32 v31, v0
	v_mov_b32_e32 v32, v0
	v_mov_b32_e32 v33, v0
	v_mov_b32_e32 v34, v0
	v_mov_b32_e32 v35, v0
	v_mov_b32_e32 v36, v0
	v_mov_b32_e32 v37, v0
	v_mov_b32_e32 v38, v0
	v_mov_b32_e32 v39, v0
	v_mov_b32_e32 v40, v0
	v_mov_b32_e32 v41, v0
	v_mov_b32_e32 v42, v0
	v_mov_b32_e32 v43, v0
	v_mov_b32_e32 v44, v0
	v_mov_b32_e32 v45, v0
	v_mov_b32_e32 v46, v0
	v_mov_b32_e32 v47, v0
	v_mov_b32_e32 v48, v0
	v_mov_b32_e32 v49, v0
	v_mov_b32_e32 v50, v0
	v_mov_b32_e32 v51, v0
	v_mov_b32_e32 v52, v0
	v_mov_b32_e32 v53, v0
	v_mov_b32_e32 v54, v0
	v_mov_b32_e32 v55, v0
	v_mov_b32_e32 v56, v0
	v_mov_b32_e32 v57, v0
	v_mov_b32_e32 v58, v0
	v_mov_b32_e32 v59, v0
	v_mov_b32_e32 v60, v0
	v_mov_b32_e32 v61, v0
	v_mov_b32_e32 v62, v0
	v_mov_b32_e32 v63, v0
	v_lshl_add_u64 v[92:93], v[78:79], 0, s[36:37]
	v_lshl_add_u64 v[94:95], v[92:93], 0, s[76:77]
	v_mov_b32_e32 v184, v94
	v_mov_b32_e32 v185, v95
	v_lshl_add_u64 v[94:95], v[92:93], 0, s[80:81]
	v_mov_b32_e32 v186, v94
	v_mov_b32_e32 v187, v95
	v_lshl_add_u64 v[94:95], v[92:93], 0, s[78:79]
	v_lshl_add_u64 v[92:93], v[92:93], 0, s[88:89]
	v_mov_b32_e32 v188, v94
	v_mov_b32_e32 v189, v95
	s_mov_b64 s[8:9], 0x2000080
	v_mov_b32_e32 v190, v92
	v_mov_b32_e32 v191, v93
	v_lshl_add_u64 v[92:93], v[80:81], 0, s[36:37]
	v_lshl_add_u64 v[94:95], v[92:93], 0, s[8:9]
	s_mov_b64 s[8:9], 0x2010080
	v_mov_b32_e32 v192, v94
	v_mov_b32_e32 v193, v95
	v_lshl_add_u64 v[94:95], v[92:93], 0, s[8:9]
	s_mov_b64 s[8:9], 0x2020080
	v_mov_b32_e32 v194, v94
	v_mov_b32_e32 v195, v95
	v_lshl_add_u64 v[94:95], v[92:93], 0, s[8:9]
	s_mov_b64 s[8:9], 0x2030080
	v_lshl_add_u64 v[92:93], v[92:93], 0, s[8:9]
	v_mov_b32_e32 v196, v94
	v_mov_b32_e32 v197, v95
	v_mov_b32_e32 v198, v92
	v_mov_b32_e32 v199, v93
	v_readfirstlane_b32 s100, v82
	s_mov_b64 vcc, 0x80
	s_waitcnt vmcnt(0) lgkmcnt(0)
	s_barrier
.LBB0_1498:
	s_and_b32 s10, s6, 0x2000
	s_xor_b32 s8, s10, 0x2000
	s_lshl_b32 s101, s8, 1
	s_add_u32 s101, s101, s100
	s_add_u32 m0, s101, 0x0
	s_nop 0
	global_load_lds_dwordx4 v[184:185], off
	s_add_u32 m0, s101, 0x1000
	v_lshl_add_u64 v[184:185], v[184:185], 0, vcc
	global_load_lds_dwordx4 v[186:187], off
	s_add_u32 m0, s101, 0x2000
	v_lshl_add_u64 v[186:187], v[186:187], 0, vcc
	global_load_lds_dwordx4 v[188:189], off
	s_add_u32 m0, s101, 0x3000
	v_lshl_add_u64 v[188:189], v[188:189], 0, vcc
	global_load_lds_dwordx4 v[190:191], off
	s_add_u32 m0, s101, 0x8000
	v_lshl_add_u64 v[190:191], v[190:191], 0, vcc
	global_load_lds_dwordx4 v[192:193], off
	s_add_u32 m0, s101, 0x9000
	v_lshl_add_u64 v[192:193], v[192:193], 0, vcc
	global_load_lds_dwordx4 v[194:195], off
	s_add_u32 m0, s101, 0xa000
	v_lshl_add_u64 v[194:195], v[194:195], 0, vcc
	global_load_lds_dwordx4 v[196:197], off
	s_add_u32 m0, s101, 0xb000
	v_lshl_add_u64 v[196:197], v[196:197], 0, vcc
	global_load_lds_dwordx4 v[198:199], off
	v_lshl_add_u64 v[198:199], v[198:199], 0, vcc
	s_lshl_b32 s8, s10, 1
	v_add_u32_e32 v68, s8, v84
	v_add_u32_e32 v140, s8, v83
	v_add_u32_e32 v120, v68, v90
	v_add_u32_e32 v136, v140, v90
	ds_read_b128 v[92:95], v120
	ds_read_b128 v[96:99], v120 offset:2048
	ds_read_b128 v[100:103], v120 offset:4096
	ds_read_b128 v[120:123], v120 offset:6144
	ds_read_b128 v[124:127], v136 offset:32768
	ds_read_b128 v[128:131], v136 offset:34816
	ds_read_b128 v[132:135], v136 offset:36864
	ds_read_b128 v[136:139], v136 offset:38912
	s_setprio 1
	s_waitcnt lgkmcnt(0)
	v_mfma_f32_16x16x32_bf16 v[60:63], v[124:127], v[92:95], v[60:63]
	v_mfma_f32_16x16x32_bf16 v[56:59], v[128:131], v[92:95], v[56:59]
	v_mfma_f32_16x16x32_bf16 v[52:55], v[132:135], v[92:95], v[52:55]
	v_mfma_f32_16x16x32_bf16 v[48:51], v[136:139], v[92:95], v[48:51]
	v_mfma_f32_16x16x32_bf16 v[44:47], v[124:127], v[96:99], v[44:47]
	v_mfma_f32_16x16x32_bf16 v[40:43], v[128:131], v[96:99], v[40:43]
	v_mfma_f32_16x16x32_bf16 v[36:39], v[132:135], v[96:99], v[36:39]
	v_mfma_f32_16x16x32_bf16 v[32:35], v[136:139], v[96:99], v[32:35]
	v_mfma_f32_16x16x32_bf16 v[28:31], v[124:127], v[100:103], v[28:31]
	v_mfma_f32_16x16x32_bf16 v[24:27], v[128:131], v[100:103], v[24:27]
	v_mfma_f32_16x16x32_bf16 v[20:23], v[132:135], v[100:103], v[20:23]
	v_mfma_f32_16x16x32_bf16 v[16:19], v[136:139], v[100:103], v[16:19]
	v_mfma_f32_16x16x32_bf16 v[12:15], v[124:127], v[120:123], v[12:15]
	v_mfma_f32_16x16x32_bf16 v[8:11], v[128:131], v[120:123], v[8:11]
	v_mfma_f32_16x16x32_bf16 v[4:7], v[132:135], v[120:123], v[4:7]
	v_mfma_f32_16x16x32_bf16 v[0:3], v[136:139], v[120:123], v[0:3]
	s_setprio 0
	v_add_u32_e32 v68, v68, v91
	ds_read_b128 v[92:95], v68
	ds_read_b128 v[96:99], v68 offset:2048
	ds_read_b128 v[100:103], v68 offset:4096
	ds_read_b128 v[120:123], v68 offset:6144
	v_add_u32_e32 v68, v140, v91
	ds_read_b128 v[124:127], v68 offset:32768
	ds_read_b128 v[128:131], v68 offset:34816
	ds_read_b128 v[132:135], v68 offset:36864
	ds_read_b128 v[136:139], v68 offset:38912
	s_setprio 1
	s_waitcnt lgkmcnt(0)
	v_mfma_f32_16x16x32_bf16 v[60:63], v[124:127], v[92:95], v[60:63]
	v_mfma_f32_16x16x32_bf16 v[56:59], v[128:131], v[92:95], v[56:59]
	v_mfma_f32_16x16x32_bf16 v[52:55], v[132:135], v[92:95], v[52:55]
	v_mfma_f32_16x16x32_bf16 v[48:51], v[136:139], v[92:95], v[48:51]
	v_mfma_f32_16x16x32_bf16 v[44:47], v[124:127], v[96:99], v[44:47]
	v_mfma_f32_16x16x32_bf16 v[40:43], v[128:131], v[96:99], v[40:43]
	v_mfma_f32_16x16x32_bf16 v[36:39], v[132:135], v[96:99], v[36:39]
	v_mfma_f32_16x16x32_bf16 v[32:35], v[136:139], v[96:99], v[32:35]
	v_mfma_f32_16x16x32_bf16 v[28:31], v[124:127], v[100:103], v[28:31]
	v_mfma_f32_16x16x32_bf16 v[24:27], v[128:131], v[100:103], v[24:27]
	v_mfma_f32_16x16x32_bf16 v[20:23], v[132:135], v[100:103], v[20:23]
	v_mfma_f32_16x16x32_bf16 v[16:19], v[136:139], v[100:103], v[16:19]
	v_mfma_f32_16x16x32_bf16 v[12:15], v[124:127], v[120:123], v[12:15]
	v_mfma_f32_16x16x32_bf16 v[8:11], v[128:131], v[120:123], v[8:11]
	v_mfma_f32_16x16x32_bf16 v[4:7], v[132:135], v[120:123], v[4:7]
	v_mfma_f32_16x16x32_bf16 v[0:3], v[136:139], v[120:123], v[0:3]
	s_setprio 0
	s_addk_i32 s6, 0x2000
	s_waitcnt vmcnt(0)
	s_add_u32 s36, s36, 0x80
	s_addc_u32 s37, s37, 0
	s_cmpk_lg_i32 s36, 0x780
	s_waitcnt vmcnt(0)
	s_barrier
	s_cbranch_scc1 .LBB0_1498
	ds_read_b128 v[78:81], v85 offset:55296
	ds_read_b128 v[92:95], v85 offset:53248
	ds_read_b128 v[96:99], v85 offset:51200
	ds_read_b128 v[100:103], v85 offset:49152
	ds_read_b128 v[120:123], v86 offset:22528
	ds_read_b128 v[124:127], v86 offset:20480
	ds_read_b128 v[128:131], v86 offset:18432
	ds_read_b128 v[132:135], v86 offset:16384
	s_setprio 1
	s_waitcnt lgkmcnt(0)
	v_mfma_f32_16x16x32_bf16 v[60:63], v[100:103], v[132:135], v[60:63]
	v_mfma_f32_16x16x32_bf16 v[56:59], v[96:99], v[132:135], v[56:59]
	v_mfma_f32_16x16x32_bf16 v[52:55], v[92:95], v[132:135], v[52:55]
	v_mfma_f32_16x16x32_bf16 v[48:51], v[78:81], v[132:135], v[48:51]
	v_mfma_f32_16x16x32_bf16 v[44:47], v[100:103], v[128:131], v[44:47]
	v_mfma_f32_16x16x32_bf16 v[40:43], v[96:99], v[128:131], v[40:43]
	v_mfma_f32_16x16x32_bf16 v[36:39], v[92:95], v[128:131], v[36:39]
	v_mfma_f32_16x16x32_bf16 v[32:35], v[78:81], v[128:131], v[32:35]
	v_mfma_f32_16x16x32_bf16 v[28:31], v[100:103], v[124:127], v[28:31]
	v_mfma_f32_16x16x32_bf16 v[24:27], v[96:99], v[124:127], v[24:27]
	v_mfma_f32_16x16x32_bf16 v[20:23], v[92:95], v[124:127], v[20:23]
	v_mfma_f32_16x16x32_bf16 v[16:19], v[78:81], v[124:127], v[16:19]
	v_mfma_f32_16x16x32_bf16 v[12:15], v[100:103], v[120:123], v[12:15]
	v_mfma_f32_16x16x32_bf16 v[8:11], v[96:99], v[120:123], v[8:11]
	v_mfma_f32_16x16x32_bf16 v[4:7], v[92:95], v[120:123], v[4:7]
	v_mfma_f32_16x16x32_bf16 v[0:3], v[78:81], v[120:123], v[0:3]
	s_setprio 0
	ds_read_b128 v[78:81], v87 offset:16384
	ds_read_b128 v[92:95], v87 offset:18432
	ds_read_b128 v[96:99], v87 offset:20480
	ds_read_b128 v[100:103], v87 offset:22528
	ds_read_b128 v[120:123], v88 offset:49152
	ds_read_b128 v[124:127], v88 offset:51200
	ds_read_b128 v[128:131], v88 offset:53248
	ds_read_b128 v[132:135], v88 offset:55296
	s_setprio 1
	s_waitcnt lgkmcnt(3)
	v_mfma_f32_16x16x32_bf16 v[60:63], v[120:123], v[78:81], v[60:63]
	s_waitcnt lgkmcnt(2)
	v_mfma_f32_16x16x32_bf16 v[56:59], v[124:127], v[78:81], v[56:59]
	s_waitcnt lgkmcnt(1)
	v_mfma_f32_16x16x32_bf16 v[52:55], v[128:131], v[78:81], v[52:55]
	s_waitcnt lgkmcnt(0)
	v_mfma_f32_16x16x32_bf16 v[48:51], v[132:135], v[78:81], v[48:51]
	v_mfma_f32_16x16x32_bf16 v[44:47], v[120:123], v[92:95], v[44:47]
	v_mfma_f32_16x16x32_bf16 v[40:43], v[124:127], v[92:95], v[40:43]
	v_mfma_f32_16x16x32_bf16 v[36:39], v[128:131], v[92:95], v[36:39]
	v_mfma_f32_16x16x32_bf16 v[32:35], v[132:135], v[92:95], v[32:35]
	v_mfma_f32_16x16x32_bf16 v[28:31], v[120:123], v[96:99], v[28:31]
	v_mfma_f32_16x16x32_bf16 v[24:27], v[124:127], v[96:99], v[24:27]
	v_mfma_f32_16x16x32_bf16 v[20:23], v[128:131], v[96:99], v[20:23]
	v_mfma_f32_16x16x32_bf16 v[16:19], v[132:135], v[96:99], v[16:19]
	v_mfma_f32_16x16x32_bf16 v[12:15], v[120:123], v[100:103], v[12:15]
	v_mfma_f32_16x16x32_bf16 v[8:11], v[124:127], v[100:103], v[8:11]
	v_mfma_f32_16x16x32_bf16 v[4:7], v[128:131], v[100:103], v[4:7]
	v_mfma_f32_16x16x32_bf16 v[0:3], v[132:135], v[100:103], v[0:3]
	s_setprio 0
	s_ashr_i32 s1, s1, 4
	s_mul_hi_i32 s6, s1, 0x4200000
	s_mul_i32 s1, s1, 0x4200000
	s_add_u32 s8, s90, s1
	v_add_u32_e32 v78, s20, v71
	s_addc_u32 s9, s91, s6
	s_and_b32 s1, s24, 0x780
	v_ashrrev_i32_e32 v79, 31, v78
	v_or_b32_e32 v68, s1, v89
	v_lshlrev_b64 v[80:81], 12, v[78:79]
	v_lshl_add_u64 v[80:81], s[8:9], 0, v[80:81]
	v_lshlrev_b32_e32 v68, 1, v68
	v_cvt_pk_bf16_f32 v60, v60, v61
	v_cvt_pk_bf16_f32 v61, v62, v63
	v_lshl_add_u64 v[62:63], v[80:81], 0, v[68:69]
	v_cvt_pk_bf16_f32 v48, v48, v49
	v_cvt_pk_bf16_f32 v49, v50, v51
	s_waitcnt vmcnt(0)
	s_barrier
	global_store_dwordx2 v[62:63], v[48:49], off offset:96
	v_or_b32_e32 v48, 16, v78
	v_ashrrev_i32_e32 v49, 31, v48
	v_lshlrev_b64 v[48:49], 12, v[48:49]
	v_lshl_add_u64 v[48:49], s[8:9], 0, v[48:49]
	v_cvt_pk_bf16_f32 v44, v44, v45
	v_cvt_pk_bf16_f32 v45, v46, v47
	v_lshl_add_u64 v[46:47], v[48:49], 0, v[68:69]
	v_cvt_pk_bf16_f32 v32, v32, v33
	v_cvt_pk_bf16_f32 v33, v34, v35
	global_store_dwordx2 v[46:47], v[32:33], off offset:96
	v_or_b32_e32 v32, 32, v78
	v_ashrrev_i32_e32 v33, 31, v32
	v_lshlrev_b64 v[32:33], 12, v[32:33]
	v_lshl_add_u64 v[32:33], s[8:9], 0, v[32:33]
	v_cvt_pk_bf16_f32 v28, v28, v29
	v_cvt_pk_bf16_f32 v29, v30, v31
	v_lshl_add_u64 v[30:31], v[32:33], 0, v[68:69]
	v_cvt_pk_bf16_f32 v16, v16, v17
	v_cvt_pk_bf16_f32 v17, v18, v19
	global_store_dwordx2 v[30:31], v[16:17], off offset:96
	v_or_b32_e32 v16, 48, v78
	v_ashrrev_i32_e32 v17, 31, v16
	v_lshlrev_b64 v[16:17], 12, v[16:17]
	v_lshl_add_u64 v[16:17], s[8:9], 0, v[16:17]
	s_add_i32 s0, s0, s84
	v_cvt_pk_bf16_f32 v56, v56, v57
	v_cvt_pk_bf16_f32 v57, v58, v59
	v_cvt_pk_bf16_f32 v52, v52, v53
	v_cvt_pk_bf16_f32 v53, v54, v55
	v_cvt_pk_bf16_f32 v40, v40, v41
	v_cvt_pk_bf16_f32 v41, v42, v43
	v_cvt_pk_bf16_f32 v36, v36, v37
	v_cvt_pk_bf16_f32 v37, v38, v39
	v_cvt_pk_bf16_f32 v24, v24, v25
	v_cvt_pk_bf16_f32 v25, v26, v27
	v_cvt_pk_bf16_f32 v20, v20, v21
	v_cvt_pk_bf16_f32 v21, v22, v23
	v_cvt_pk_bf16_f32 v12, v12, v13
	v_cvt_pk_bf16_f32 v13, v14, v15
	v_lshl_add_u64 v[14:15], v[16:17], 0, v[68:69]
	v_cvt_pk_bf16_f32 v8, v8, v9
	v_cvt_pk_bf16_f32 v9, v10, v11
	v_cvt_pk_bf16_f32 v4, v4, v5
	v_cvt_pk_bf16_f32 v5, v6, v7
	v_cvt_pk_bf16_f32 v0, v0, v1
	v_cvt_pk_bf16_f32 v1, v2, v3
	s_cmpk_lt_i32 s0, 0x18c0
	global_store_dwordx2 v[62:63], v[60:61], off
	global_store_dwordx2 v[62:63], v[56:57], off offset:32
	global_store_dwordx2 v[62:63], v[52:53], off offset:64
	global_store_dwordx2 v[46:47], v[44:45], off
	global_store_dwordx2 v[46:47], v[40:41], off offset:32
	global_store_dwordx2 v[46:47], v[36:37], off offset:64
	global_store_dwordx2 v[30:31], v[28:29], off
	global_store_dwordx2 v[30:31], v[24:25], off offset:32
	global_store_dwordx2 v[30:31], v[20:21], off offset:64
	global_store_dwordx2 v[14:15], v[12:13], off
	global_store_dwordx2 v[14:15], v[8:9], off offset:32
	global_store_dwordx2 v[14:15], v[4:5], off offset:64
	global_store_dwordx2 v[14:15], v[0:1], off offset:96
	s_cbranch_scc1 .LBB0_1497

.LBB0_1706:
	s_and_b32 s0, s12, 7
	v_readlane_b32 s8, v180, 8
	s_mul_i32 s0, s0, s8
	s_ashr_i32 s1, s12, 3
	s_add_i32 s0, s0, s1
	s_ashr_i32 s1, s0, 31
	s_lshr_b32 s1, s1, 26
	s_add_i32 s1, s0, s1
	s_ashr_i32 s6, s1, 6
	s_lshl_b32 s6, s6, 3
	s_sub_i32 s8, s8, s6
	s_min_i32 s8, s8, 8
	s_abs_i32 s9, s8
	v_cvt_f32_u32_e32 v0, s9
	s_sub_i32 s11, 0, s9
	s_andn2_b32 s1, s1, 63
	s_sub_i32 s0, s0, s1
	v_rcp_iflag_f32_e32 v0, v0
	s_abs_i32 s1, s0
	s_xor_b32 s10, s0, s8
	s_ashr_i32 s10, s10, 31
	v_mul_f32_e32 v0, 0x4f7ffffe, v0
	v_cvt_u32_f32_e32 v0, v0
	v_add_u32_e32 v6, 0x1000, v68
	s_mov_b64 s[22:23], 0x40000
	s_mov_b64 s[36:37], 0x60000
	v_readfirstlane_b32 s13, v0
	s_mul_i32 s11, s11, s13
	s_mul_hi_u32 s11, s13, s11
	s_add_i32 s13, s13, s11
	s_mul_hi_u32 s11, s1, s13
	s_mul_i32 s13, s11, s9
	s_sub_i32 s1, s1, s13
	s_add_i32 s18, s11, 1
	s_sub_i32 s13, s1, s9
	s_cmp_ge_u32 s1, s9
	s_cselect_b32 s11, s18, s11
	s_cselect_b32 s1, s13, s1
	s_add_i32 s13, s11, 1
	s_cmp_ge_u32 s1, s9
	s_cselect_b32 s1, s13, s11
	s_xor_b32 s1, s1, s10
	s_sub_i32 s9, s1, s10
	s_mul_i32 s1, s9, s8
	s_sub_i32 s0, s0, s1
	s_add_i32 s1, s6, s0
	s_lshl_b32 s24, s1, 7
	s_ashr_i32 s25, s24, 31
	s_lshl_b32 s20, s9, 7
	s_lshl_b64 s[8:9], s[24:25], 12
	v_readfirstlane_b32 s0, v68
	v_lshl_add_u64 v[0:1], v[72:73], 0, s[8:9]
	s_mov_b32 m0, s0
	v_readfirstlane_b32 s0, v6
	v_add_u32_e32 v6, 0x2000, v68
	global_load_lds_dwordx4 v[0:1], off
	v_lshl_add_u64 v[4:5], v[0:1], 0, s[28:29]
	s_mov_b32 m0, s0
	v_readfirstlane_b32 s0, v6
	global_load_lds_dwordx4 v[4:5], off
	v_lshl_add_u64 v[4:5], v[0:1], 0, s[22:23]
	s_mov_b32 m0, s0
	v_lshl_add_u64 v[0:1], v[0:1], 0, s[36:37]
	global_load_lds_dwordx4 v[4:5], off
	v_add_u32_e32 v4, 0x3000, v68
	s_ashr_i32 s21, s20, 31
	v_readfirstlane_b32 s0, v4
	s_mov_b32 m0, s0
	s_lshl_b64 s[10:11], s[20:21], 12
	global_load_lds_dwordx4 v[0:1], off
	v_add_u32_e32 v0, 0x8000, v68
	v_add_u32_e32 v4, 0x9000, v68
	v_readfirstlane_b32 s0, v0
	v_lshl_add_u64 v[2:3], v[74:75], 0, s[10:11]
	s_mov_b32 m0, s0
	v_readfirstlane_b32 s0, v4
	v_add_u32_e32 v4, 0xa000, v68
	global_load_lds_dwordx4 v[2:3], off
	v_lshl_add_u64 v[0:1], v[2:3], 0, s[28:29]
	s_mov_b32 m0, s0
	v_readfirstlane_b32 s0, v4
	global_load_lds_dwordx4 v[0:1], off
	v_lshl_add_u64 v[0:1], v[2:3], 0, s[22:23]
	s_mov_b32 m0, s0
	v_lshl_add_u64 v[86:87], v[84:85], 0, s[8:9]
	global_load_lds_dwordx4 v[0:1], off
	v_lshl_add_u64 v[0:1], v[2:3], 0, s[36:37]
	v_add_u32_e32 v2, 0xb000, v68
	v_lshl_add_u64 v[88:89], v[84:85], 0, s[10:11]
	v_readfirstlane_b32 s0, v2
	s_mov_b32 m0, s0
	s_mov_b32 s0, 0
	global_load_lds_dwordx4 v[0:1], off
	s_waitcnt vmcnt(0)
	v_mov_b32_e32 v0, 0
	s_mov_b64 s[36:37], 0
	v_mov_b32_e32 v1, v0
	v_mov_b32_e32 v2, v0
	v_mov_b32_e32 v3, v0
	v_mov_b32_e32 v4, v0
	v_mov_b32_e32 v5, v0
	v_mov_b32_e32 v6, v0
	v_mov_b32_e32 v7, v0
	v_mov_b32_e32 v8, v0
	v_mov_b32_e32 v9, v0
	v_mov_b32_e32 v10, v0
	v_mov_b32_e32 v11, v0
	v_mov_b32_e32 v12, v0
	v_mov_b32_e32 v13, v0
	v_mov_b32_e32 v14, v0
	v_mov_b32_e32 v15, v0
	v_mov_b32_e32 v16, v0
	v_mov_b32_e32 v17, v0
	v_mov_b32_e32 v18, v0
	v_mov_b32_e32 v19, v0
	v_mov_b32_e32 v20, v0
	v_mov_b32_e32 v21, v0
	v_mov_b32_e32 v22, v0
	v_mov_b32_e32 v23, v0
	v_mov_b32_e32 v24, v0
	v_mov_b32_e32 v25, v0
	v_mov_b32_e32 v26, v0
	v_mov_b32_e32 v27, v0
	v_mov_b32_e32 v28, v0
	v_mov_b32_e32 v29, v0
	v_mov_b32_e32 v30, v0
	v_mov_b32_e32 v31, v0
	v_mov_b32_e32 v32, v0
	v_mov_b32_e32 v33, v0
	v_mov_b32_e32 v34, v0
	v_mov_b32_e32 v35, v0
	v_mov_b32_e32 v36, v0
	v_mov_b32_e32 v37, v0
	v_mov_b32_e32 v38, v0
	v_mov_b32_e32 v39, v0
	v_mov_b32_e32 v40, v0
	v_mov_b32_e32 v41, v0
	v_mov_b32_e32 v42, v0
	v_mov_b32_e32 v43, v0
	v_mov_b32_e32 v44, v0
	v_mov_b32_e32 v45, v0
	v_mov_b32_e32 v46, v0
	v_mov_b32_e32 v47, v0
	v_mov_b32_e32 v48, v0
	v_mov_b32_e32 v49, v0
	v_mov_b32_e32 v50, v0
	v_mov_b32_e32 v51, v0
	v_mov_b32_e32 v52, v0
	v_mov_b32_e32 v53, v0
	v_mov_b32_e32 v54, v0
	v_mov_b32_e32 v55, v0
	v_mov_b32_e32 v56, v0
	v_mov_b32_e32 v57, v0
	v_mov_b32_e32 v58, v0
	v_mov_b32_e32 v59, v0
	v_mov_b32_e32 v60, v0
	v_mov_b32_e32 v61, v0
	v_mov_b32_e32 v62, v0
	v_mov_b32_e32 v63, v0
	v_lshl_add_u64 v[98:99], v[86:87], 0, s[36:37]
	s_mov_b64 s[8:9], 0x7100080
	v_lshl_add_u64 v[100:101], v[98:99], 0, s[8:9]
	s_mov_b64 s[8:9], 0x7120080
	v_mov_b32_e32 v184, v100
	v_mov_b32_e32 v185, v101
	v_lshl_add_u64 v[100:101], v[98:99], 0, s[8:9]
	s_mov_b64 s[8:9], 0x7140080
	v_mov_b32_e32 v186, v100
	v_mov_b32_e32 v187, v101
	v_lshl_add_u64 v[100:101], v[98:99], 0, s[8:9]
	s_mov_b64 s[8:9], 0x7160080
	v_mov_b32_e32 v188, v100
	v_mov_b32_e32 v189, v101
	v_lshl_add_u64 v[98:99], v[98:99], 0, s[8:9]
	s_mov_b64 s[8:9], 0x2c00080
	v_mov_b32_e32 v190, v98
	v_mov_b32_e32 v191, v99
	v_lshl_add_u64 v[98:99], v[88:89], 0, s[36:37]
	v_lshl_add_u64 v[100:101], v[98:99], 0, s[8:9]
	s_mov_b64 s[8:9], 0x2c20080
	v_mov_b32_e32 v192, v100
	v_mov_b32_e32 v193, v101
	v_lshl_add_u64 v[100:101], v[98:99], 0, s[8:9]
	s_mov_b64 s[8:9], 0x2c40080
	v_mov_b32_e32 v194, v100
	v_mov_b32_e32 v195, v101
	v_lshl_add_u64 v[100:101], v[98:99], 0, s[8:9]
	s_mov_b64 s[8:9], 0x2c60080
	v_mov_b32_e32 v196, v100
	v_mov_b32_e32 v197, v101
	v_lshl_add_u64 v[98:99], v[98:99], 0, s[8:9]
	v_mov_b32_e32 v198, v98
	v_mov_b32_e32 v199, v99
	v_readfirstlane_b32 s100, v68
	s_mov_b64 vcc, 0x80
	s_waitcnt vmcnt(0) lgkmcnt(0)
	s_barrier
.LBB0_1707:
	s_and_b32 s6, s0, 0x2000
	s_xor_b32 s8, s6, 0x2000
	s_lshl_b32 s101, s8, 1
	s_add_u32 s101, s101, s100
	s_add_u32 m0, s101, 0x0
	s_nop 0
	global_load_lds_dwordx4 v[184:185], off
	s_add_u32 m0, s101, 0x1000
	v_lshl_add_u64 v[184:185], v[184:185], 0, vcc
	global_load_lds_dwordx4 v[186:187], off
	s_add_u32 m0, s101, 0x2000
	v_lshl_add_u64 v[186:187], v[186:187], 0, vcc
	global_load_lds_dwordx4 v[188:189], off
	s_add_u32 m0, s101, 0x3000
	v_lshl_add_u64 v[188:189], v[188:189], 0, vcc
	global_load_lds_dwordx4 v[190:191], off
	s_add_u32 m0, s101, 0x8000
	v_lshl_add_u64 v[190:191], v[190:191], 0, vcc
	global_load_lds_dwordx4 v[192:193], off
	s_add_u32 m0, s101, 0x9000
	v_lshl_add_u64 v[192:193], v[192:193], 0, vcc
	global_load_lds_dwordx4 v[194:195], off
	s_add_u32 m0, s101, 0xa000
	v_lshl_add_u64 v[194:195], v[194:195], 0, vcc
	global_load_lds_dwordx4 v[196:197], off
	s_add_u32 m0, s101, 0xb000
	v_lshl_add_u64 v[196:197], v[196:197], 0, vcc
	global_load_lds_dwordx4 v[198:199], off
	v_lshl_add_u64 v[198:199], v[198:199], 0, vcc
	s_lshl_b32 s6, s6, 1
	v_add_u32_e32 v102, s6, v90
	v_add_u32_e32 v103, s6, v71
	v_add_u32_e32 v128, v102, v96
	v_add_u32_e32 v144, v103, v96
	ds_read_b128 v[98:101], v128
	ds_read_b128 v[120:123], v128 offset:2048
	ds_read_b128 v[124:127], v128 offset:4096
	ds_read_b128 v[128:131], v128 offset:6144
	ds_read_b128 v[132:135], v144 offset:32768
	ds_read_b128 v[136:139], v144 offset:34816
	ds_read_b128 v[140:143], v144 offset:36864
	ds_read_b128 v[144:147], v144 offset:38912
	s_setprio 1
	s_waitcnt lgkmcnt(0)
	v_mfma_f32_16x16x32_bf16 v[60:63], v[132:135], v[98:101], v[60:63]
	v_mfma_f32_16x16x32_bf16 v[56:59], v[136:139], v[98:101], v[56:59]
	v_mfma_f32_16x16x32_bf16 v[52:55], v[140:143], v[98:101], v[52:55]
	v_mfma_f32_16x16x32_bf16 v[48:51], v[144:147], v[98:101], v[48:51]
	v_mfma_f32_16x16x32_bf16 v[44:47], v[132:135], v[120:123], v[44:47]
	v_mfma_f32_16x16x32_bf16 v[40:43], v[136:139], v[120:123], v[40:43]
	v_mfma_f32_16x16x32_bf16 v[36:39], v[140:143], v[120:123], v[36:39]
	v_mfma_f32_16x16x32_bf16 v[32:35], v[144:147], v[120:123], v[32:35]
	v_mfma_f32_16x16x32_bf16 v[28:31], v[132:135], v[124:127], v[28:31]
	v_mfma_f32_16x16x32_bf16 v[24:27], v[136:139], v[124:127], v[24:27]
	v_mfma_f32_16x16x32_bf16 v[20:23], v[140:143], v[124:127], v[20:23]
	v_mfma_f32_16x16x32_bf16 v[16:19], v[144:147], v[124:127], v[16:19]
	v_mfma_f32_16x16x32_bf16 v[12:15], v[132:135], v[128:131], v[12:15]
	v_mfma_f32_16x16x32_bf16 v[8:11], v[136:139], v[128:131], v[8:11]
	v_mfma_f32_16x16x32_bf16 v[4:7], v[140:143], v[128:131], v[4:7]
	v_mfma_f32_16x16x32_bf16 v[0:3], v[144:147], v[128:131], v[0:3]
	s_setprio 0
	v_add_u32_e32 v102, v102, v97
	ds_read_b128 v[98:101], v102
	ds_read_b128 v[120:123], v102 offset:2048
	ds_read_b128 v[124:127], v102 offset:4096
	ds_read_b128 v[128:131], v102 offset:6144
	v_add_u32_e32 v102, v103, v97
	ds_read_b128 v[132:135], v102 offset:32768
	ds_read_b128 v[136:139], v102 offset:34816
	ds_read_b128 v[140:143], v102 offset:36864
	ds_read_b128 v[144:147], v102 offset:38912
	s_setprio 1
	s_waitcnt lgkmcnt(0)
	v_mfma_f32_16x16x32_bf16 v[60:63], v[132:135], v[98:101], v[60:63]
	v_mfma_f32_16x16x32_bf16 v[56:59], v[136:139], v[98:101], v[56:59]
	v_mfma_f32_16x16x32_bf16 v[52:55], v[140:143], v[98:101], v[52:55]
	v_mfma_f32_16x16x32_bf16 v[48:51], v[144:147], v[98:101], v[48:51]
	v_mfma_f32_16x16x32_bf16 v[44:47], v[132:135], v[120:123], v[44:47]
	v_mfma_f32_16x16x32_bf16 v[40:43], v[136:139], v[120:123], v[40:43]
	v_mfma_f32_16x16x32_bf16 v[36:39], v[140:143], v[120:123], v[36:39]
	v_mfma_f32_16x16x32_bf16 v[32:35], v[144:147], v[120:123], v[32:35]
	v_mfma_f32_16x16x32_bf16 v[28:31], v[132:135], v[124:127], v[28:31]
	v_mfma_f32_16x16x32_bf16 v[24:27], v[136:139], v[124:127], v[24:27]
	v_mfma_f32_16x16x32_bf16 v[20:23], v[140:143], v[124:127], v[20:23]
	v_mfma_f32_16x16x32_bf16 v[16:19], v[144:147], v[124:127], v[16:19]
	v_mfma_f32_16x16x32_bf16 v[12:15], v[132:135], v[128:131], v[12:15]
	v_mfma_f32_16x16x32_bf16 v[8:11], v[136:139], v[128:131], v[8:11]
	v_mfma_f32_16x16x32_bf16 v[4:7], v[140:143], v[128:131], v[4:7]
	v_mfma_f32_16x16x32_bf16 v[0:3], v[144:147], v[128:131], v[0:3]
	s_setprio 0
	s_waitcnt vmcnt(0)
	s_add_u32 s36, s36, 0x80
	s_addc_u32 s37, s37, 0
	s_addk_i32 s0, 0x2000
	s_cmpk_lg_i32 s36, 0xf80
	s_waitcnt vmcnt(0)
	s_barrier
	s_cbranch_scc1 .LBB0_1707
	ds_read_b128 v[86:89], v92 offset:16384
	ds_read_b128 v[98:101], v92 offset:18432
	ds_read_b128 v[120:123], v92 offset:20480
	ds_read_b128 v[124:127], v92 offset:22528
	ds_read_b128 v[128:131], v93 offset:49152
	ds_read_b128 v[132:135], v93 offset:51200
	ds_read_b128 v[136:139], v93 offset:53248
	ds_read_b128 v[140:143], v93 offset:55296
	s_setprio 1
	s_waitcnt lgkmcnt(3)
	v_mfma_f32_16x16x32_bf16 v[60:63], v[128:131], v[86:89], v[60:63]
	s_waitcnt lgkmcnt(2)
	v_mfma_f32_16x16x32_bf16 v[56:59], v[132:135], v[86:89], v[56:59]
	s_waitcnt lgkmcnt(1)
	v_mfma_f32_16x16x32_bf16 v[52:55], v[136:139], v[86:89], v[52:55]
	s_waitcnt lgkmcnt(0)
	v_mfma_f32_16x16x32_bf16 v[48:51], v[140:143], v[86:89], v[48:51]
	v_mfma_f32_16x16x32_bf16 v[40:43], v[132:135], v[98:101], v[40:43]
	v_mfma_f32_16x16x32_bf16 v[36:39], v[136:139], v[98:101], v[36:39]
	v_mfma_f32_16x16x32_bf16 v[32:35], v[140:143], v[98:101], v[32:35]
	v_mfma_f32_16x16x32_bf16 v[20:23], v[136:139], v[120:123], v[20:23]
	v_mfma_f32_16x16x32_bf16 v[16:19], v[140:143], v[120:123], v[16:19]
	v_mfma_f32_16x16x32_bf16 v[0:3], v[140:143], v[124:127], v[0:3]
	v_mfma_f32_16x16x32_bf16 v[86:89], v[128:131], v[98:101], v[44:47]
	v_mfma_f32_16x16x32_bf16 v[98:101], v[128:131], v[120:123], v[28:31]
	v_mfma_f32_16x16x32_bf16 v[144:147], v[132:135], v[120:123], v[24:27]
	v_mfma_f32_16x16x32_bf16 v[120:123], v[128:131], v[124:127], v[12:15]
	v_mfma_f32_16x16x32_bf16 v[128:131], v[132:135], v[124:127], v[8:11]
	v_mfma_f32_16x16x32_bf16 v[132:135], v[136:139], v[124:127], v[4:7]
	s_setprio 0
	s_nop 1
	ds_read_b128 v[4:7], v94 offset:16384
	ds_read_b128 v[8:11], v94 offset:18432
	ds_read_b128 v[124:127], v94 offset:20480
	ds_read_b128 v[136:139], v94 offset:22528
	ds_read_b128 v[140:143], v95 offset:49152
	ds_read_b128 v[148:151], v95 offset:51200
	ds_read_b128 v[152:155], v95 offset:53248
	ds_read_b128 v[156:159], v95 offset:55296
	s_setprio 1
	s_waitcnt lgkmcnt(3)
	v_mfma_f32_16x16x32_bf16 v[60:63], v[140:143], v[4:7], v[60:63]
	s_waitcnt lgkmcnt(2)
	v_mfma_f32_16x16x32_bf16 v[44:47], v[148:151], v[4:7], v[56:59]
	s_waitcnt lgkmcnt(1)
	v_mfma_f32_16x16x32_bf16 v[28:31], v[152:155], v[4:7], v[52:55]
	s_waitcnt lgkmcnt(0)
	v_mfma_f32_16x16x32_bf16 v[12:15], v[156:159], v[4:7], v[48:51]
	v_mfma_f32_16x16x32_bf16 v[56:59], v[140:143], v[8:11], v[86:89]
	v_mfma_f32_16x16x32_bf16 v[40:43], v[148:151], v[8:11], v[40:43]
	v_mfma_f32_16x16x32_bf16 v[24:27], v[152:155], v[8:11], v[36:39]
	v_mfma_f32_16x16x32_bf16 v[8:11], v[156:159], v[8:11], v[32:35]
	v_mfma_f32_16x16x32_bf16 v[52:55], v[140:143], v[124:127], v[98:101]
	v_mfma_f32_16x16x32_bf16 v[36:39], v[148:151], v[124:127], v[144:147]
	v_mfma_f32_16x16x32_bf16 v[20:23], v[152:155], v[124:127], v[20:23]
	v_mfma_f32_16x16x32_bf16 v[4:7], v[156:159], v[124:127], v[16:19]
	v_mfma_f32_16x16x32_bf16 v[48:51], v[140:143], v[136:139], v[120:123]
	v_mfma_f32_16x16x32_bf16 v[32:35], v[148:151], v[136:139], v[128:131]
	v_mfma_f32_16x16x32_bf16 v[16:19], v[152:155], v[136:139], v[132:135]
	v_mfma_f32_16x16x32_bf16 v[0:3], v[156:159], v[136:139], v[0:3]
	s_setprio 0
	s_waitcnt vmcnt(0)
	s_cmpk_gt_i32 s1, 0x7f
	s_barrier
	s_cbranch_scc0 .LBB0_1710
	s_add_i32 s0, s24, 0xffffc000
	s_lshr_b32 s0, s0, 8
	v_readlane_b32 s6, v180, 24
	s_add_i32 s6, s0, s6
	s_and_b32 s10, s24, 0x80
	s_lshl_b64 s[8:9], s[6:7], 8
	v_readlane_b32 s36, v182, 19
	s_or_b32 s8, s8, s10
	s_mov_b64 s[10:11], 0
	v_readlane_b32 s37, v182, 20
	s_branch .LBB0_1711
